# P3 epilogues: row-scale loads of the 8 row groups batched (gate: one batch of 8, head: 2 batches of 4) so groups no longer drain vmcnt(0) behind their stores; head variant packs into one quad
# speedup vs baseline: 1.0058x; 1.0058x over previous
; __device__ __forceinline__ unsigned cvt_pk_bf16(float lo, float hi) { unsigned r; asm volatile("v_cvt_pk_bf16_f32 %0, %1, %2" : "=v"(r) : "v"(lo), "v"(hi)); return r; }
; __device__ __forceinline__ float sigmoidf_(float x) { return __builtin_amdgcn_rcpf(1.f + __builtin_amdgcn_exp2f(-x * LOG2E)); }
;     __device__ __forceinline__ void operator()(const f32x4 (&acc)[2][2][4][2], const pg8::Unit& u, int wr, int wc, int fr, int fq) const {
;     ...
;         if (u.pn >= 12) {
;             const int col0 = (u.pn - 12) * 256 + wc * 32 + 4 * fq;
; #pragma unroll
;             for (int ai = 0; ai < 2; ++ai)
; #pragma unroll
;                 for (int m = 0; m < 4; ++m) { const int row = row0 + ai * 128 + m * 16; const float rs = __builtin_amdgcn_rsqf(ss[row] * (1.f / DM) + EPS);
; #pragma unroll
;                     for (int bj = 0; bj < 2; ++bj)
; #pragma unroll
;                         for (int n = 0; n < 2; ++n) { const f32x4 a = acc[ai][bj][m][n] * rs; u32x2 w; w.x = cvt_pk_bf16(sigmoidf_(a[0]), sigmoidf_(a[1])); w.y = cvt_pk_bf16(sigmoidf_(a[2]), sigmoidf_(a[3]));
;                             *(u32x2*)(G + (size_t)row * 2048 + col0 + bj * 128 + n * 16) = w; } }
;             return;
.LBB0_605:
	s_and_b64 vcc, exec, s[0:1]
	s_cbranch_vccz .LBB0_722
	v_ashrrev_i32_e32 v167, 31, v166
	v_lshl_add_u64 v[134:135], v[166:167], 2, s[26:27]
	global_load_dword v150, v[134:135], off
	global_load_dword v151, v[134:135], off offset:64
	global_load_dword v152, v[134:135], off offset:128
	global_load_dword v153, v[134:135], off offset:192
	global_load_dword v154, v[134:135], off offset:512
	global_load_dword v155, v[134:135], off offset:576
	global_load_dword v156, v[134:135], off offset:640
	global_load_dword v157, v[134:135], off offset:704
	v_lshl_add_u32 v0, s48, 8, v234
	v_lshlrev_b64 v[138:139], 1, v[0:1]
	v_and_b32_e32 v190, 4, v204
	v_mul_u32_u24_e32 v190, 6, v190
	v_add_u32_e32 v138, v138, v190
	v_lshlrev_b64 v[136:137], 12, v[166:167]
	v_lshl_add_u64 v[136:137], s[28:29], 0, v[136:137]
	v_lshl_add_u64 v[136:137], v[136:137], 0, v[138:139]
	v_or_b32_e32 v140, 16, v166
	v_ashrrev_i32_e32 v141, 31, v140
	s_mov_b32 s3, 0x80000
	s_mov_b64 s[0:1], 0x80000
	s_waitcnt vmcnt(0)
	v_mov_b32_e32 v142, v150
	v_fmamk_f32 v0, v142, 0x3a800000, v236
	v_rsq_f32_e32 v0, v0
	v_lshl_add_u64 v[142:143], v[140:141], 2, s[26:27]
	v_pk_mul_f32 v[132:133], v[132:133], v[0:1] op_sel_hi:[1,0]
	v_pk_mul_f32 v[130:131], v[130:131], v[0:1] op_sel_hi:[1,0]
	v_pk_mul_f32 v[118:119], v[118:119], v[0:1] op_sel_hi:[1,0]
	v_pk_mul_f32 v[128:129], v[128:129], v[0:1] op_sel_hi:[1,0]
	v_pk_mul_f32 v[126:127], v[126:127], v[0:1] op_sel_hi:[1,0]
	v_pk_mul_f32 v[124:125], v[124:125], v[0:1] op_sel_hi:[1,0]
	v_pk_mul_f32 v[122:123], v[122:123], v[0:1] op_sel_hi:[1,0]
	v_pk_mul_f32 v[120:121], v[120:121], v[0:1] op_sel_hi:[1,0]
	v_mul_f32_e32 v0, 0xbfb8aa3b, v130
	v_mul_f32_e32 v130, 0xbfb8aa3b, v131
	v_mul_f32_e32 v131, 0xbfb8aa3b, v132
	v_mul_f32_e32 v132, 0xbfb8aa3b, v133
	v_mul_f32_e32 v118, 0xbfb8aa3b, v118
	v_mul_f32_e32 v119, 0xbfb8aa3b, v119
	v_mul_f32_e32 v126, 0xbfb8aa3b, v126
	v_mul_f32_e32 v127, 0xbfb8aa3b, v127
	v_mul_f32_e32 v128, 0xbfb8aa3b, v128
	v_mul_f32_e32 v129, 0xbfb8aa3b, v129
	v_exp_f32_e32 v0, v0
	v_exp_f32_e32 v130, v130
	v_exp_f32_e32 v131, v131
	v_exp_f32_e32 v132, v132
	v_exp_f32_e32 v118, v118
	v_exp_f32_e32 v119, v119
	v_mul_f32_e32 v122, 0xbfb8aa3b, v122
	v_mul_f32_e32 v123, 0xbfb8aa3b, v123
	v_mul_f32_e32 v124, 0xbfb8aa3b, v124
	v_mul_f32_e32 v125, 0xbfb8aa3b, v125
	v_exp_f32_e32 v126, v126
	v_exp_f32_e32 v127, v127
	v_exp_f32_e32 v128, v128
	v_exp_f32_e32 v129, v129
	v_mul_f32_e32 v120, 0xbfb8aa3b, v120
	v_mul_f32_e32 v121, 0xbfb8aa3b, v121
	v_exp_f32_e32 v122, v122
	v_exp_f32_e32 v123, v123
	v_exp_f32_e32 v124, v124
	v_exp_f32_e32 v125, v125
	v_exp_f32_e32 v120, v120
	v_exp_f32_e32 v121, v121
	v_add_f32_e32 v0, 1.0, v0
	v_add_f32_e32 v130, 1.0, v130
	v_add_f32_e32 v131, 1.0, v131
	v_add_f32_e32 v132, 1.0, v132
	v_add_f32_e32 v118, 1.0, v118
	v_add_f32_e32 v119, 1.0, v119
	v_add_f32_e32 v126, 1.0, v126
	v_add_f32_e32 v127, 1.0, v127
	v_add_f32_e32 v128, 1.0, v128
	v_add_f32_e32 v129, 1.0, v129
	v_rcp_f32_e32 v0, v0
	v_rcp_f32_e32 v130, v130
	v_rcp_f32_e32 v131, v131
	v_rcp_f32_e32 v132, v132
	v_rcp_f32_e32 v133, v118
	v_rcp_f32_e32 v144, v119
	v_cvt_pk_bf16_f32 v190, v0, v130
	v_cvt_pk_bf16_f32 v191, v131, v132
	v_add_f32_e32 v122, 1.0, v122
	v_add_f32_e32 v123, 1.0, v123
	v_add_f32_e32 v124, 1.0, v124
	v_add_f32_e32 v125, 1.0, v125
	v_rcp_f32_e32 v126, v126
	v_rcp_f32_e32 v127, v127
	v_rcp_f32_e32 v128, v128
	v_rcp_f32_e32 v129, v129
	v_cvt_pk_bf16_f32 v192, v126, v127
	v_cvt_pk_bf16_f32 v193, v128, v129
	v_add_f32_e32 v120, 1.0, v120
	v_add_f32_e32 v121, 1.0, v121
	v_rcp_f32_e32 v122, v122
	v_rcp_f32_e32 v123, v123
	v_rcp_f32_e32 v124, v124
	v_rcp_f32_e32 v125, v125
	v_cvt_pk_bf16_f32 v194, v122, v123
	v_cvt_pk_bf16_f32 v195, v124, v125
	v_rcp_f32_e32 v120, v120
	v_rcp_f32_e32 v121, v121
	v_cvt_pk_bf16_f32 v196, v133, v144
	v_cvt_pk_bf16_f32 v197, v120, v121
	s_nop 1
	v_permlane16_swap_b32_e32 v190, v192
	v_permlane16_swap_b32_e32 v191, v193
	v_permlane16_swap_b32_e32 v194, v196
	v_permlane16_swap_b32_e32 v195, v197
	global_store_dwordx4 v[136:137], v[190:193], off
	global_store_dwordx4 v[136:137], v[194:197], off offset:256
	v_lshlrev_b64 v[122:123], 12, v[140:141]
	v_lshl_add_u64 v[122:123], s[28:29], 0, v[122:123]
	v_lshl_add_u64 v[122:123], v[122:123], 0, v[138:139]
	v_or_b32_e32 v118, 32, v166
	v_ashrrev_i32_e32 v119, 31, v118
	v_lshl_add_u64 v[120:121], v[118:119], 2, s[26:27]
	v_mov_b32_e32 v0, v151
	v_fmamk_f32 v0, v0, 0x3a800000, v236
	v_rsq_f32_e32 v0, v0
	s_nop 0
	v_pk_mul_f32 v[116:117], v[116:117], v[0:1] op_sel_hi:[1,0]
	v_pk_mul_f32 v[114:115], v[114:115], v[0:1] op_sel_hi:[1,0]
	v_pk_mul_f32 v[102:103], v[102:103], v[0:1] op_sel_hi:[1,0]
	v_pk_mul_f32 v[112:113], v[112:113], v[0:1] op_sel_hi:[1,0]
	v_pk_mul_f32 v[110:111], v[110:111], v[0:1] op_sel_hi:[1,0]
	v_pk_mul_f32 v[108:109], v[108:109], v[0:1] op_sel_hi:[1,0]
	v_pk_mul_f32 v[106:107], v[106:107], v[0:1] op_sel_hi:[1,0]
	v_pk_mul_f32 v[104:105], v[104:105], v[0:1] op_sel_hi:[1,0]
	v_mul_f32_e32 v0, 0xbfb8aa3b, v114
	v_mul_f32_e32 v114, 0xbfb8aa3b, v115
	v_mul_f32_e32 v115, 0xbfb8aa3b, v116
	v_mul_f32_e32 v116, 0xbfb8aa3b, v117
	v_mul_f32_e32 v102, 0xbfb8aa3b, v102
	v_mul_f32_e32 v103, 0xbfb8aa3b, v103
	v_mul_f32_e32 v110, 0xbfb8aa3b, v110
	v_mul_f32_e32 v111, 0xbfb8aa3b, v111
	v_mul_f32_e32 v112, 0xbfb8aa3b, v112
	v_mul_f32_e32 v113, 0xbfb8aa3b, v113
	v_exp_f32_e32 v0, v0
	v_exp_f32_e32 v114, v114
	v_exp_f32_e32 v115, v115
	v_exp_f32_e32 v116, v116
	v_exp_f32_e32 v102, v102
	v_exp_f32_e32 v103, v103
	v_mul_f32_e32 v106, 0xbfb8aa3b, v106
	v_mul_f32_e32 v107, 0xbfb8aa3b, v107
	v_mul_f32_e32 v108, 0xbfb8aa3b, v108
	v_mul_f32_e32 v109, 0xbfb8aa3b, v109
; __device__ __forceinline__ unsigned cvt_pk_bf16(float lo, float hi) { unsigned r; asm volatile("v_cvt_pk_bf16_f32 %0, %1, %2" : "=v"(r) : "v"(lo), "v"(hi)); return r; }
; __device__ __forceinline__ float sigmoidf_(float x) { return __builtin_amdgcn_rcpf(1.f + __builtin_amdgcn_exp2f(-x * LOG2E)); }
;     __device__ __forceinline__ void operator()(const f32x4 (&acc)[2][2][4][2], const pg8::Unit& u, int wr, int wc, int fr, int fq) const {
;     ...
;                 for (int m = 0; m < 4; ++m) { const int row = row0 + ai * 128 + m * 16; const float rs = __builtin_amdgcn_rsqf(ss[row] * (1.f / DM) + EPS);
; #pragma unroll
;                     for (int bj = 0; bj < 2; ++bj)
; #pragma unroll
;                         for (int n = 0; n < 2; ++n) { const f32x4 a = acc[ai][bj][m][n] * rs; u32x2 w; w.x = cvt_pk_bf16(sigmoidf_(a[0]), sigmoidf_(a[1])); w.y = cvt_pk_bf16(sigmoidf_(a[2]), sigmoidf_(a[3]));
;                             *(u32x2*)(G + (size_t)row * 2048 + col0 + bj * 128 + n * 16) = w; } }
	v_exp_f32_e32 v110, v110
	v_exp_f32_e32 v111, v111
	v_exp_f32_e32 v112, v112
	v_exp_f32_e32 v113, v113
	v_mul_f32_e32 v104, 0xbfb8aa3b, v104
	v_mul_f32_e32 v105, 0xbfb8aa3b, v105
	v_exp_f32_e32 v106, v106
	v_exp_f32_e32 v107, v107
	v_exp_f32_e32 v108, v108
	v_exp_f32_e32 v109, v109
	v_exp_f32_e32 v104, v104
	v_exp_f32_e32 v105, v105
	v_add_f32_e32 v0, 1.0, v0
	v_add_f32_e32 v114, 1.0, v114
	v_add_f32_e32 v115, 1.0, v115
	v_add_f32_e32 v116, 1.0, v116
	v_add_f32_e32 v102, 1.0, v102
	v_add_f32_e32 v103, 1.0, v103
	v_add_f32_e32 v110, 1.0, v110
	v_add_f32_e32 v111, 1.0, v111
	v_add_f32_e32 v112, 1.0, v112
	v_add_f32_e32 v113, 1.0, v113
	v_rcp_f32_e32 v0, v0
	v_rcp_f32_e32 v114, v114
	v_rcp_f32_e32 v115, v115
	v_rcp_f32_e32 v116, v116
	v_rcp_f32_e32 v117, v102
	v_rcp_f32_e32 v124, v103
	v_cvt_pk_bf16_f32 v190, v0, v114
	v_cvt_pk_bf16_f32 v191, v115, v116
	v_add_f32_e32 v106, 1.0, v106
	v_add_f32_e32 v107, 1.0, v107
	v_add_f32_e32 v108, 1.0, v108
	v_add_f32_e32 v109, 1.0, v109
	v_rcp_f32_e32 v110, v110
	v_rcp_f32_e32 v111, v111
	v_rcp_f32_e32 v112, v112
	v_rcp_f32_e32 v113, v113
	v_cvt_pk_bf16_f32 v192, v110, v111
	v_cvt_pk_bf16_f32 v193, v112, v113
	v_add_f32_e32 v104, 1.0, v104
	v_add_f32_e32 v105, 1.0, v105
	v_rcp_f32_e32 v106, v106
	v_rcp_f32_e32 v107, v107
	v_rcp_f32_e32 v108, v108
	v_rcp_f32_e32 v109, v109
	v_cvt_pk_bf16_f32 v194, v106, v107
	v_cvt_pk_bf16_f32 v195, v108, v109
	v_rcp_f32_e32 v104, v104
	v_rcp_f32_e32 v105, v105
	v_cvt_pk_bf16_f32 v196, v117, v124
	v_cvt_pk_bf16_f32 v197, v104, v105
	s_nop 1
	v_permlane16_swap_b32_e32 v190, v192
	v_permlane16_swap_b32_e32 v191, v193
	v_permlane16_swap_b32_e32 v194, v196
	v_permlane16_swap_b32_e32 v195, v197
	global_store_dwordx4 v[122:123], v[190:193], off
	global_store_dwordx4 v[122:123], v[194:197], off offset:256
	v_lshlrev_b64 v[106:107], 12, v[118:119]
	v_lshl_add_u64 v[106:107], s[28:29], 0, v[106:107]
	v_lshl_add_u64 v[106:107], v[106:107], 0, v[138:139]
	v_or_b32_e32 v102, 48, v166
	v_ashrrev_i32_e32 v103, 31, v102
	v_lshl_add_u64 v[104:105], v[102:103], 2, s[26:27]
	v_mov_b32_e32 v0, v152
	v_fmamk_f32 v0, v0, 0x3a800000, v236
	v_rsq_f32_e32 v0, v0
	s_nop 0
	v_pk_mul_f32 v[100:101], v[100:101], v[0:1] op_sel_hi:[1,0]
	v_pk_mul_f32 v[98:99], v[98:99], v[0:1] op_sel_hi:[1,0]
	v_pk_mul_f32 v[86:87], v[86:87], v[0:1] op_sel_hi:[1,0]
	v_pk_mul_f32 v[96:97], v[96:97], v[0:1] op_sel_hi:[1,0]
	v_pk_mul_f32 v[94:95], v[94:95], v[0:1] op_sel_hi:[1,0]
	v_pk_mul_f32 v[92:93], v[92:93], v[0:1] op_sel_hi:[1,0]
	v_pk_mul_f32 v[90:91], v[90:91], v[0:1] op_sel_hi:[1,0]
	v_pk_mul_f32 v[88:89], v[88:89], v[0:1] op_sel_hi:[1,0]
	v_mul_f32_e32 v0, 0xbfb8aa3b, v98
	v_mul_f32_e32 v98, 0xbfb8aa3b, v99
	v_mul_f32_e32 v99, 0xbfb8aa3b, v100
	v_mul_f32_e32 v100, 0xbfb8aa3b, v101
	v_mul_f32_e32 v86, 0xbfb8aa3b, v86
	v_mul_f32_e32 v87, 0xbfb8aa3b, v87
	v_mul_f32_e32 v94, 0xbfb8aa3b, v94
	v_mul_f32_e32 v95, 0xbfb8aa3b, v95
	v_mul_f32_e32 v96, 0xbfb8aa3b, v96
	v_mul_f32_e32 v97, 0xbfb8aa3b, v97
	v_exp_f32_e32 v0, v0
	v_exp_f32_e32 v98, v98
	v_exp_f32_e32 v99, v99
	v_exp_f32_e32 v100, v100
	v_exp_f32_e32 v86, v86
	v_exp_f32_e32 v87, v87
	v_mul_f32_e32 v90, 0xbfb8aa3b, v90
	v_mul_f32_e32 v91, 0xbfb8aa3b, v91
	v_mul_f32_e32 v92, 0xbfb8aa3b, v92
	v_mul_f32_e32 v93, 0xbfb8aa3b, v93
	v_exp_f32_e32 v94, v94
	v_exp_f32_e32 v95, v95
	v_exp_f32_e32 v96, v96
	v_exp_f32_e32 v97, v97
	v_mul_f32_e32 v88, 0xbfb8aa3b, v88
	v_mul_f32_e32 v89, 0xbfb8aa3b, v89
	v_exp_f32_e32 v90, v90
	v_exp_f32_e32 v91, v91
	v_exp_f32_e32 v92, v92
	v_exp_f32_e32 v93, v93
	v_exp_f32_e32 v88, v88
	v_exp_f32_e32 v89, v89
	v_add_f32_e32 v0, 1.0, v0
	v_add_f32_e32 v98, 1.0, v98
	v_add_f32_e32 v99, 1.0, v99
	v_add_f32_e32 v100, 1.0, v100
	v_add_f32_e32 v86, 1.0, v86
	v_add_f32_e32 v87, 1.0, v87
	v_add_f32_e32 v94, 1.0, v94
	v_add_f32_e32 v95, 1.0, v95
	v_add_f32_e32 v96, 1.0, v96
	v_add_f32_e32 v97, 1.0, v97
	v_rcp_f32_e32 v0, v0
	v_rcp_f32_e32 v98, v98
	v_rcp_f32_e32 v99, v99
	v_rcp_f32_e32 v100, v100
	v_rcp_f32_e32 v101, v86
	v_rcp_f32_e32 v108, v87
	v_cvt_pk_bf16_f32 v190, v0, v98
	v_cvt_pk_bf16_f32 v191, v99, v100
	v_add_f32_e32 v90, 1.0, v90
	v_add_f32_e32 v91, 1.0, v91
	v_add_f32_e32 v92, 1.0, v92
	v_add_f32_e32 v93, 1.0, v93
	v_rcp_f32_e32 v94, v94
	v_rcp_f32_e32 v95, v95
	v_rcp_f32_e32 v96, v96
	v_rcp_f32_e32 v97, v97
	v_cvt_pk_bf16_f32 v192, v94, v95
	v_cvt_pk_bf16_f32 v193, v96, v97
	v_add_f32_e32 v88, 1.0, v88
	v_add_f32_e32 v89, 1.0, v89
	v_rcp_f32_e32 v90, v90
	v_rcp_f32_e32 v91, v91
	v_rcp_f32_e32 v92, v92
	v_rcp_f32_e32 v93, v93
	v_cvt_pk_bf16_f32 v194, v90, v91
	v_cvt_pk_bf16_f32 v195, v92, v93
	v_rcp_f32_e32 v88, v88
	v_rcp_f32_e32 v89, v89
	v_cvt_pk_bf16_f32 v196, v101, v108
	v_cvt_pk_bf16_f32 v197, v88, v89
	s_nop 1
	v_permlane16_swap_b32_e32 v190, v192
	v_permlane16_swap_b32_e32 v191, v193
	v_permlane16_swap_b32_e32 v194, v196
	v_permlane16_swap_b32_e32 v195, v197
	global_store_dwordx4 v[106:107], v[190:193], off
	global_store_dwordx4 v[106:107], v[194:197], off offset:256
	v_lshlrev_b64 v[86:87], 12, v[102:103]
	v_lshl_add_u64 v[86:87], s[28:29], 0, v[86:87]
	v_lshl_add_u64 v[86:87], v[86:87], 0, v[138:139]
	v_mov_b32_e32 v0, v153
	v_fmamk_f32 v0, v0, 0x3a800000, v236
	v_rsq_f32_e32 v0, v0
	s_nop 0
	v_pk_mul_f32 v[84:85], v[84:85], v[0:1] op_sel_hi:[1,0]
	v_pk_mul_f32 v[82:83], v[82:83], v[0:1] op_sel_hi:[1,0]
	v_pk_mul_f32 v[70:71], v[70:71], v[0:1] op_sel_hi:[1,0]
	v_pk_mul_f32 v[80:81], v[80:81], v[0:1] op_sel_hi:[1,0]
	v_pk_mul_f32 v[78:79], v[78:79], v[0:1] op_sel_hi:[1,0]
	v_pk_mul_f32 v[76:77], v[76:77], v[0:1] op_sel_hi:[1,0]
	v_pk_mul_f32 v[74:75], v[74:75], v[0:1] op_sel_hi:[1,0]
	v_pk_mul_f32 v[72:73], v[72:73], v[0:1] op_sel_hi:[1,0]
; __device__ __forceinline__ unsigned cvt_pk_bf16(float lo, float hi) { unsigned r; asm volatile("v_cvt_pk_bf16_f32 %0, %1, %2" : "=v"(r) : "v"(lo), "v"(hi)); return r; }
; __device__ __forceinline__ float sigmoidf_(float x) { return __builtin_amdgcn_rcpf(1.f + __builtin_amdgcn_exp2f(-x * LOG2E)); }
;     __device__ __forceinline__ void operator()(const f32x4 (&acc)[2][2][4][2], const pg8::Unit& u, int wr, int wc, int fr, int fq) const {
;     ...
;                 for (int m = 0; m < 4; ++m) { const int row = row0 + ai * 128 + m * 16; const float rs = __builtin_amdgcn_rsqf(ss[row] * (1.f / DM) + EPS);
; #pragma unroll
;                     for (int bj = 0; bj < 2; ++bj)
; #pragma unroll
;                         for (int n = 0; n < 2; ++n) { const f32x4 a = acc[ai][bj][m][n] * rs; u32x2 w; w.x = cvt_pk_bf16(sigmoidf_(a[0]), sigmoidf_(a[1])); w.y = cvt_pk_bf16(sigmoidf_(a[2]), sigmoidf_(a[3]));
;                             *(u32x2*)(G + (size_t)row * 2048 + col0 + bj * 128 + n * 16) = w; } }
	v_mul_f32_e32 v0, 0xbfb8aa3b, v82
	v_mul_f32_e32 v82, 0xbfb8aa3b, v83
	v_mul_f32_e32 v83, 0xbfb8aa3b, v84
	v_mul_f32_e32 v84, 0xbfb8aa3b, v85
	v_mul_f32_e32 v70, 0xbfb8aa3b, v70
	v_mul_f32_e32 v71, 0xbfb8aa3b, v71
	v_mul_f32_e32 v78, 0xbfb8aa3b, v78
	v_mul_f32_e32 v79, 0xbfb8aa3b, v79
	v_mul_f32_e32 v80, 0xbfb8aa3b, v80
	v_mul_f32_e32 v81, 0xbfb8aa3b, v81
	v_exp_f32_e32 v0, v0
	v_exp_f32_e32 v82, v82
	v_exp_f32_e32 v83, v83
	v_exp_f32_e32 v84, v84
	v_exp_f32_e32 v70, v70
	v_exp_f32_e32 v71, v71
	v_mul_f32_e32 v74, 0xbfb8aa3b, v74
	v_mul_f32_e32 v75, 0xbfb8aa3b, v75
	v_mul_f32_e32 v76, 0xbfb8aa3b, v76
	v_mul_f32_e32 v77, 0xbfb8aa3b, v77
	v_exp_f32_e32 v78, v78
	v_exp_f32_e32 v79, v79
	v_exp_f32_e32 v80, v80
	v_exp_f32_e32 v81, v81
	v_mul_f32_e32 v72, 0xbfb8aa3b, v72
	v_mul_f32_e32 v73, 0xbfb8aa3b, v73
	v_exp_f32_e32 v74, v74
	v_exp_f32_e32 v75, v75
	v_exp_f32_e32 v76, v76
	v_exp_f32_e32 v77, v77
	v_exp_f32_e32 v72, v72
	v_exp_f32_e32 v73, v73
	v_add_f32_e32 v0, 1.0, v0
	v_add_f32_e32 v82, 1.0, v82
	v_add_f32_e32 v83, 1.0, v83
	v_add_f32_e32 v84, 1.0, v84
	v_add_f32_e32 v70, 1.0, v70
	v_add_f32_e32 v71, 1.0, v71
	v_add_f32_e32 v78, 1.0, v78
	v_add_f32_e32 v79, 1.0, v79
	v_add_f32_e32 v80, 1.0, v80
	v_add_f32_e32 v81, 1.0, v81
	v_rcp_f32_e32 v0, v0
	v_rcp_f32_e32 v82, v82
	v_rcp_f32_e32 v83, v83
	v_rcp_f32_e32 v84, v84
	v_rcp_f32_e32 v85, v70
	v_rcp_f32_e32 v88, v71
	v_cvt_pk_bf16_f32 v190, v0, v82
	v_cvt_pk_bf16_f32 v191, v83, v84
	v_add_f32_e32 v74, 1.0, v74
	v_add_f32_e32 v75, 1.0, v75
	v_add_f32_e32 v76, 1.0, v76
	v_add_f32_e32 v77, 1.0, v77
	v_rcp_f32_e32 v78, v78
	v_rcp_f32_e32 v79, v79
	v_rcp_f32_e32 v80, v80
	v_rcp_f32_e32 v81, v81
	v_cvt_pk_bf16_f32 v192, v78, v79
	v_cvt_pk_bf16_f32 v193, v80, v81
	v_add_f32_e32 v72, 1.0, v72
	v_add_f32_e32 v73, 1.0, v73
	v_rcp_f32_e32 v74, v74
	v_rcp_f32_e32 v75, v75
	v_rcp_f32_e32 v76, v76
	v_rcp_f32_e32 v77, v77
	v_cvt_pk_bf16_f32 v194, v74, v75
	v_cvt_pk_bf16_f32 v195, v76, v77
	v_rcp_f32_e32 v72, v72
	v_rcp_f32_e32 v73, v73
	v_cvt_pk_bf16_f32 v196, v85, v88
	v_cvt_pk_bf16_f32 v197, v72, v73
	s_nop 1
	v_permlane16_swap_b32_e32 v190, v192
	v_permlane16_swap_b32_e32 v191, v193
	v_permlane16_swap_b32_e32 v194, v196
	v_permlane16_swap_b32_e32 v195, v197
	global_store_dwordx4 v[86:87], v[190:193], off
	global_store_dwordx4 v[86:87], v[194:197], off offset:256
	v_add_co_u32_e32 v72, vcc, s3, v136
	v_lshl_add_u64 v[70:71], v[136:137], 0, s[0:1]
	s_nop 0
	v_addc_co_u32_e32 v73, vcc, 0, v137, vcc
	s_mov_b32 s3, 0x90000
	s_mov_b64 s[0:1], 0x90000
	v_mov_b32_e32 v0, v154
	v_fmamk_f32 v0, v0, 0x3a800000, v236
	v_rsq_f32_e32 v0, v0
	s_nop 0
	v_pk_mul_f32 v[68:69], v[68:69], v[0:1] op_sel_hi:[1,0]
	v_pk_mul_f32 v[66:67], v[66:67], v[0:1] op_sel_hi:[1,0]
	v_pk_mul_f32 v[54:55], v[54:55], v[0:1] op_sel_hi:[1,0]
	v_pk_mul_f32 v[64:65], v[64:65], v[0:1] op_sel_hi:[1,0]
	v_pk_mul_f32 v[62:63], v[62:63], v[0:1] op_sel_hi:[1,0]
	v_pk_mul_f32 v[60:61], v[60:61], v[0:1] op_sel_hi:[1,0]
	v_pk_mul_f32 v[58:59], v[58:59], v[0:1] op_sel_hi:[1,0]
	v_pk_mul_f32 v[56:57], v[56:57], v[0:1] op_sel_hi:[1,0]
	v_mul_f32_e32 v0, 0xbfb8aa3b, v66
	v_mul_f32_e32 v66, 0xbfb8aa3b, v67
	v_mul_f32_e32 v67, 0xbfb8aa3b, v68
	v_mul_f32_e32 v68, 0xbfb8aa3b, v69
	v_mul_f32_e32 v54, 0xbfb8aa3b, v54
	v_mul_f32_e32 v55, 0xbfb8aa3b, v55
	v_mul_f32_e32 v62, 0xbfb8aa3b, v62
	v_mul_f32_e32 v63, 0xbfb8aa3b, v63
	v_mul_f32_e32 v64, 0xbfb8aa3b, v64
	v_mul_f32_e32 v65, 0xbfb8aa3b, v65
	v_exp_f32_e32 v0, v0
	v_exp_f32_e32 v66, v66
	v_exp_f32_e32 v67, v67
	v_exp_f32_e32 v68, v68
	v_exp_f32_e32 v54, v54
	v_exp_f32_e32 v55, v55
	v_mul_f32_e32 v58, 0xbfb8aa3b, v58
	v_mul_f32_e32 v59, 0xbfb8aa3b, v59
	v_mul_f32_e32 v60, 0xbfb8aa3b, v60
	v_mul_f32_e32 v61, 0xbfb8aa3b, v61
	v_exp_f32_e32 v62, v62
	v_exp_f32_e32 v63, v63
	v_exp_f32_e32 v64, v64
	v_exp_f32_e32 v65, v65
	v_mul_f32_e32 v56, 0xbfb8aa3b, v56
	v_mul_f32_e32 v57, 0xbfb8aa3b, v57
	v_exp_f32_e32 v58, v58
	v_exp_f32_e32 v59, v59
	v_exp_f32_e32 v60, v60
	v_exp_f32_e32 v61, v61
	v_exp_f32_e32 v56, v56
	v_exp_f32_e32 v57, v57
	v_add_f32_e32 v0, 1.0, v0
	v_add_f32_e32 v66, 1.0, v66
	v_add_f32_e32 v67, 1.0, v67
	v_add_f32_e32 v68, 1.0, v68
	v_add_f32_e32 v54, 1.0, v54
	v_add_f32_e32 v55, 1.0, v55
	v_add_f32_e32 v62, 1.0, v62
	v_add_f32_e32 v63, 1.0, v63
	v_add_f32_e32 v64, 1.0, v64
	v_add_f32_e32 v65, 1.0, v65
	v_rcp_f32_e32 v0, v0
	v_rcp_f32_e32 v66, v66
	v_rcp_f32_e32 v67, v67
	v_rcp_f32_e32 v68, v68
	v_rcp_f32_e32 v69, v54
	v_rcp_f32_e32 v74, v55
	v_cvt_pk_bf16_f32 v190, v0, v66
	v_cvt_pk_bf16_f32 v191, v67, v68
	v_add_f32_e32 v58, 1.0, v58
	v_add_f32_e32 v59, 1.0, v59
	v_add_f32_e32 v60, 1.0, v60
	v_add_f32_e32 v61, 1.0, v61
	v_rcp_f32_e32 v62, v62
	v_rcp_f32_e32 v63, v63
	v_rcp_f32_e32 v64, v64
	v_rcp_f32_e32 v65, v65
	v_cvt_pk_bf16_f32 v192, v62, v63
	v_cvt_pk_bf16_f32 v193, v64, v65
	v_add_f32_e32 v56, 1.0, v56
	v_add_f32_e32 v57, 1.0, v57
	v_rcp_f32_e32 v58, v58
	v_rcp_f32_e32 v59, v59
	v_rcp_f32_e32 v60, v60
	v_rcp_f32_e32 v61, v61
	v_cvt_pk_bf16_f32 v194, v58, v59
	v_cvt_pk_bf16_f32 v195, v60, v61
	v_rcp_f32_e32 v56, v56
	v_rcp_f32_e32 v57, v57
	v_cvt_pk_bf16_f32 v196, v69, v74
	v_cvt_pk_bf16_f32 v197, v56, v57
	s_nop 1
	v_permlane16_swap_b32_e32 v190, v192
	v_permlane16_swap_b32_e32 v191, v193
	v_permlane16_swap_b32_e32 v194, v196
	v_permlane16_swap_b32_e32 v195, v197
	global_store_dwordx4 v[70:71], v[190:193], off
	global_store_dwordx4 v[70:71], v[194:197], off offset:256
	v_add_co_u32_e32 v56, vcc, s3, v136
	v_lshl_add_u64 v[54:55], v[136:137], 0, s[0:1]
	s_nop 0
	v_addc_co_u32_e32 v57, vcc, 0, v137, vcc
	s_mov_b32 s3, 0xa0000
	s_mov_b64 s[0:1], 0xa0000
	v_mov_b32_e32 v0, v155
; __device__ __forceinline__ unsigned cvt_pk_bf16(float lo, float hi) { unsigned r; asm volatile("v_cvt_pk_bf16_f32 %0, %1, %2" : "=v"(r) : "v"(lo), "v"(hi)); return r; }
; __device__ __forceinline__ float sigmoidf_(float x) { return __builtin_amdgcn_rcpf(1.f + __builtin_amdgcn_exp2f(-x * LOG2E)); }
;     __device__ __forceinline__ void operator()(const f32x4 (&acc)[2][2][4][2], const pg8::Unit& u, int wr, int wc, int fr, int fq) const {
;     ...
;                 for (int m = 0; m < 4; ++m) { const int row = row0 + ai * 128 + m * 16; const float rs = __builtin_amdgcn_rsqf(ss[row] * (1.f / DM) + EPS);
; #pragma unroll
;                     for (int bj = 0; bj < 2; ++bj)
; #pragma unroll
;                         for (int n = 0; n < 2; ++n) { const f32x4 a = acc[ai][bj][m][n] * rs; u32x2 w; w.x = cvt_pk_bf16(sigmoidf_(a[0]), sigmoidf_(a[1])); w.y = cvt_pk_bf16(sigmoidf_(a[2]), sigmoidf_(a[3]));
;                             *(u32x2*)(G + (size_t)row * 2048 + col0 + bj * 128 + n * 16) = w; } }
	v_fmamk_f32 v0, v0, 0x3a800000, v236
	v_rsq_f32_e32 v0, v0
	s_nop 0
	v_pk_mul_f32 v[52:53], v[52:53], v[0:1] op_sel_hi:[1,0]
	v_pk_mul_f32 v[50:51], v[50:51], v[0:1] op_sel_hi:[1,0]
	v_pk_mul_f32 v[38:39], v[38:39], v[0:1] op_sel_hi:[1,0]
	v_pk_mul_f32 v[48:49], v[48:49], v[0:1] op_sel_hi:[1,0]
	v_pk_mul_f32 v[46:47], v[46:47], v[0:1] op_sel_hi:[1,0]
	v_pk_mul_f32 v[44:45], v[44:45], v[0:1] op_sel_hi:[1,0]
	v_pk_mul_f32 v[42:43], v[42:43], v[0:1] op_sel_hi:[1,0]
	v_pk_mul_f32 v[40:41], v[40:41], v[0:1] op_sel_hi:[1,0]
	v_mul_f32_e32 v0, 0xbfb8aa3b, v50
	v_mul_f32_e32 v50, 0xbfb8aa3b, v51
	v_mul_f32_e32 v51, 0xbfb8aa3b, v52
	v_mul_f32_e32 v52, 0xbfb8aa3b, v53
	v_mul_f32_e32 v38, 0xbfb8aa3b, v38
	v_mul_f32_e32 v39, 0xbfb8aa3b, v39
	v_mul_f32_e32 v46, 0xbfb8aa3b, v46
	v_mul_f32_e32 v47, 0xbfb8aa3b, v47
	v_mul_f32_e32 v48, 0xbfb8aa3b, v48
	v_mul_f32_e32 v49, 0xbfb8aa3b, v49
	v_exp_f32_e32 v0, v0
	v_exp_f32_e32 v50, v50
	v_exp_f32_e32 v51, v51
	v_exp_f32_e32 v52, v52
	v_exp_f32_e32 v38, v38
	v_exp_f32_e32 v39, v39
	v_mul_f32_e32 v42, 0xbfb8aa3b, v42
	v_mul_f32_e32 v43, 0xbfb8aa3b, v43
	v_mul_f32_e32 v44, 0xbfb8aa3b, v44
	v_mul_f32_e32 v45, 0xbfb8aa3b, v45
	v_exp_f32_e32 v46, v46
	v_exp_f32_e32 v47, v47
	v_exp_f32_e32 v48, v48
	v_exp_f32_e32 v49, v49
	v_mul_f32_e32 v40, 0xbfb8aa3b, v40
	v_mul_f32_e32 v41, 0xbfb8aa3b, v41
	v_exp_f32_e32 v42, v42
	v_exp_f32_e32 v43, v43
	v_exp_f32_e32 v44, v44
	v_exp_f32_e32 v45, v45
	v_exp_f32_e32 v40, v40
	v_exp_f32_e32 v41, v41
	v_add_f32_e32 v0, 1.0, v0
	v_add_f32_e32 v50, 1.0, v50
	v_add_f32_e32 v51, 1.0, v51
	v_add_f32_e32 v52, 1.0, v52
	v_add_f32_e32 v38, 1.0, v38
	v_add_f32_e32 v39, 1.0, v39
	v_add_f32_e32 v46, 1.0, v46
	v_add_f32_e32 v47, 1.0, v47
	v_add_f32_e32 v48, 1.0, v48
	v_add_f32_e32 v49, 1.0, v49
	v_rcp_f32_e32 v0, v0
	v_rcp_f32_e32 v50, v50
	v_rcp_f32_e32 v51, v51
	v_rcp_f32_e32 v52, v52
	v_rcp_f32_e32 v53, v38
	v_rcp_f32_e32 v58, v39
	v_cvt_pk_bf16_f32 v190, v0, v50
	v_cvt_pk_bf16_f32 v191, v51, v52
	v_add_f32_e32 v42, 1.0, v42
	v_add_f32_e32 v43, 1.0, v43
	v_add_f32_e32 v44, 1.0, v44
	v_add_f32_e32 v45, 1.0, v45
	v_rcp_f32_e32 v46, v46
	v_rcp_f32_e32 v47, v47
	v_rcp_f32_e32 v48, v48
	v_rcp_f32_e32 v49, v49
	v_cvt_pk_bf16_f32 v192, v46, v47
	v_cvt_pk_bf16_f32 v193, v48, v49
	v_add_f32_e32 v40, 1.0, v40
	v_add_f32_e32 v41, 1.0, v41
	v_rcp_f32_e32 v42, v42
	v_rcp_f32_e32 v43, v43
	v_rcp_f32_e32 v44, v44
	v_rcp_f32_e32 v45, v45
	v_cvt_pk_bf16_f32 v194, v42, v43
	v_cvt_pk_bf16_f32 v195, v44, v45
	v_rcp_f32_e32 v40, v40
	v_rcp_f32_e32 v41, v41
	v_cvt_pk_bf16_f32 v196, v53, v58
	v_cvt_pk_bf16_f32 v197, v40, v41
	s_nop 1
	v_permlane16_swap_b32_e32 v190, v192
	v_permlane16_swap_b32_e32 v191, v193
	v_permlane16_swap_b32_e32 v194, v196
	v_permlane16_swap_b32_e32 v195, v197
	global_store_dwordx4 v[54:55], v[190:193], off
	global_store_dwordx4 v[54:55], v[194:197], off offset:256
	v_add_co_u32_e32 v40, vcc, s3, v136
	v_lshl_add_u64 v[38:39], v[136:137], 0, s[0:1]
	s_nop 0
	v_addc_co_u32_e32 v41, vcc, 0, v137, vcc
	s_mov_b32 s3, 0xb0000
	s_mov_b64 s[0:1], 0xb0000
	v_mov_b32_e32 v0, v156
	v_fmamk_f32 v0, v0, 0x3a800000, v236
	v_rsq_f32_e32 v0, v0
	s_nop 0
	v_pk_mul_f32 v[36:37], v[36:37], v[0:1] op_sel_hi:[1,0]
	v_pk_mul_f32 v[34:35], v[34:35], v[0:1] op_sel_hi:[1,0]
	v_pk_mul_f32 v[22:23], v[22:23], v[0:1] op_sel_hi:[1,0]
	v_pk_mul_f32 v[32:33], v[32:33], v[0:1] op_sel_hi:[1,0]
	v_pk_mul_f32 v[30:31], v[30:31], v[0:1] op_sel_hi:[1,0]
	v_pk_mul_f32 v[28:29], v[28:29], v[0:1] op_sel_hi:[1,0]
	v_pk_mul_f32 v[26:27], v[26:27], v[0:1] op_sel_hi:[1,0]
	v_pk_mul_f32 v[24:25], v[24:25], v[0:1] op_sel_hi:[1,0]
	v_mul_f32_e32 v0, 0xbfb8aa3b, v34
	v_mul_f32_e32 v34, 0xbfb8aa3b, v35
	v_mul_f32_e32 v35, 0xbfb8aa3b, v36
	v_mul_f32_e32 v36, 0xbfb8aa3b, v37
	v_mul_f32_e32 v22, 0xbfb8aa3b, v22
	v_mul_f32_e32 v23, 0xbfb8aa3b, v23
	v_mul_f32_e32 v30, 0xbfb8aa3b, v30
	v_mul_f32_e32 v31, 0xbfb8aa3b, v31
	v_mul_f32_e32 v32, 0xbfb8aa3b, v32
	v_mul_f32_e32 v33, 0xbfb8aa3b, v33
	v_exp_f32_e32 v0, v0
	v_exp_f32_e32 v34, v34
	v_exp_f32_e32 v35, v35
	v_exp_f32_e32 v36, v36
	v_exp_f32_e32 v22, v22
	v_exp_f32_e32 v23, v23
	v_mul_f32_e32 v26, 0xbfb8aa3b, v26
	v_mul_f32_e32 v27, 0xbfb8aa3b, v27
	v_mul_f32_e32 v28, 0xbfb8aa3b, v28
	v_mul_f32_e32 v29, 0xbfb8aa3b, v29
	v_exp_f32_e32 v30, v30
	v_exp_f32_e32 v31, v31
	v_exp_f32_e32 v32, v32
	v_exp_f32_e32 v33, v33
	v_mul_f32_e32 v24, 0xbfb8aa3b, v24
	v_mul_f32_e32 v25, 0xbfb8aa3b, v25
	v_exp_f32_e32 v26, v26
	v_exp_f32_e32 v27, v27
	v_exp_f32_e32 v28, v28
	v_exp_f32_e32 v29, v29
; __device__ __forceinline__ unsigned cvt_pk_bf16(float lo, float hi) { unsigned r; asm volatile("v_cvt_pk_bf16_f32 %0, %1, %2" : "=v"(r) : "v"(lo), "v"(hi)); return r; }
; __device__ __forceinline__ float sigmoidf_(float x) { return __builtin_amdgcn_rcpf(1.f + __builtin_amdgcn_exp2f(-x * LOG2E)); }
;     __device__ __forceinline__ void operator()(const f32x4 (&acc)[2][2][4][2], const pg8::Unit& u, int wr, int wc, int fr, int fq) const {
;     ...
;                 for (int m = 0; m < 4; ++m) { const int row = row0 + ai * 128 + m * 16; const float rs = __builtin_amdgcn_rsqf(ss[row] * (1.f / DM) + EPS);
; #pragma unroll
;                     for (int bj = 0; bj < 2; ++bj)
; #pragma unroll
;                         for (int n = 0; n < 2; ++n) { const f32x4 a = acc[ai][bj][m][n] * rs; u32x2 w; w.x = cvt_pk_bf16(sigmoidf_(a[0]), sigmoidf_(a[1])); w.y = cvt_pk_bf16(sigmoidf_(a[2]), sigmoidf_(a[3]));
;                             *(u32x2*)(G + (size_t)row * 2048 + col0 + bj * 128 + n * 16) = w; } }
	v_exp_f32_e32 v24, v24
	v_exp_f32_e32 v25, v25
	v_add_f32_e32 v0, 1.0, v0
	v_add_f32_e32 v34, 1.0, v34
	v_add_f32_e32 v35, 1.0, v35
	v_add_f32_e32 v36, 1.0, v36
	v_add_f32_e32 v22, 1.0, v22
	v_add_f32_e32 v23, 1.0, v23
	v_add_f32_e32 v30, 1.0, v30
	v_add_f32_e32 v31, 1.0, v31
	v_add_f32_e32 v32, 1.0, v32
	v_add_f32_e32 v33, 1.0, v33
	v_rcp_f32_e32 v0, v0
	v_rcp_f32_e32 v34, v34
	v_rcp_f32_e32 v35, v35
	v_rcp_f32_e32 v36, v36
	v_rcp_f32_e32 v37, v22
	v_rcp_f32_e32 v42, v23
	v_cvt_pk_bf16_f32 v190, v0, v34
	v_cvt_pk_bf16_f32 v191, v35, v36
	v_add_f32_e32 v26, 1.0, v26
	v_add_f32_e32 v27, 1.0, v27
	v_add_f32_e32 v28, 1.0, v28
	v_add_f32_e32 v29, 1.0, v29
	v_rcp_f32_e32 v30, v30
	v_rcp_f32_e32 v31, v31
	v_rcp_f32_e32 v32, v32
	v_rcp_f32_e32 v33, v33
	v_cvt_pk_bf16_f32 v192, v30, v31
	v_cvt_pk_bf16_f32 v193, v32, v33
	v_add_f32_e32 v24, 1.0, v24
	v_add_f32_e32 v25, 1.0, v25
	v_rcp_f32_e32 v26, v26
	v_rcp_f32_e32 v27, v27
	v_rcp_f32_e32 v28, v28
	v_rcp_f32_e32 v29, v29
	v_cvt_pk_bf16_f32 v194, v26, v27
	v_cvt_pk_bf16_f32 v195, v28, v29
	v_rcp_f32_e32 v24, v24
	v_rcp_f32_e32 v25, v25
	v_cvt_pk_bf16_f32 v196, v37, v42
	v_cvt_pk_bf16_f32 v197, v24, v25
	s_nop 1
	v_permlane16_swap_b32_e32 v190, v192
	v_permlane16_swap_b32_e32 v191, v193
	v_permlane16_swap_b32_e32 v194, v196
	v_permlane16_swap_b32_e32 v195, v197
	global_store_dwordx4 v[38:39], v[190:193], off
	global_store_dwordx4 v[38:39], v[194:197], off offset:256
	v_add_co_u32_e32 v24, vcc, s3, v136
	v_lshl_add_u64 v[22:23], v[136:137], 0, s[0:1]
	s_nop 0
	v_addc_co_u32_e32 v25, vcc, 0, v137, vcc
	v_mov_b32_e32 v0, v157
	v_fmamk_f32 v0, v0, 0x3a800000, v236
	v_rsq_f32_e32 v0, v0
	s_nop 0
	v_pk_mul_f32 v[20:21], v[20:21], v[0:1] op_sel_hi:[1,0]
	v_pk_mul_f32 v[18:19], v[18:19], v[0:1] op_sel_hi:[1,0]
	v_pk_mul_f32 v[6:7], v[6:7], v[0:1] op_sel_hi:[1,0]
	v_pk_mul_f32 v[16:17], v[16:17], v[0:1] op_sel_hi:[1,0]
	v_pk_mul_f32 v[14:15], v[14:15], v[0:1] op_sel_hi:[1,0]
	v_pk_mul_f32 v[12:13], v[12:13], v[0:1] op_sel_hi:[1,0]
	v_pk_mul_f32 v[10:11], v[10:11], v[0:1] op_sel_hi:[1,0]
	v_pk_mul_f32 v[8:9], v[8:9], v[0:1] op_sel_hi:[1,0]
	v_mul_f32_e32 v0, 0xbfb8aa3b, v18
	v_mul_f32_e32 v18, 0xbfb8aa3b, v19
	v_mul_f32_e32 v19, 0xbfb8aa3b, v20
	v_mul_f32_e32 v20, 0xbfb8aa3b, v21
	v_mul_f32_e32 v6, 0xbfb8aa3b, v6
	v_mul_f32_e32 v7, 0xbfb8aa3b, v7
	v_mul_f32_e32 v14, 0xbfb8aa3b, v14
	v_mul_f32_e32 v15, 0xbfb8aa3b, v15
	v_mul_f32_e32 v16, 0xbfb8aa3b, v16
	v_mul_f32_e32 v17, 0xbfb8aa3b, v17
	v_exp_f32_e32 v0, v0
	v_exp_f32_e32 v18, v18
	v_exp_f32_e32 v19, v19
	v_exp_f32_e32 v20, v20
	v_exp_f32_e32 v6, v6
	v_exp_f32_e32 v7, v7
	v_mul_f32_e32 v10, 0xbfb8aa3b, v10
	v_mul_f32_e32 v11, 0xbfb8aa3b, v11
	v_mul_f32_e32 v12, 0xbfb8aa3b, v12
	v_mul_f32_e32 v13, 0xbfb8aa3b, v13
	v_exp_f32_e32 v14, v14
	v_exp_f32_e32 v15, v15
	v_exp_f32_e32 v16, v16
	v_exp_f32_e32 v17, v17
	v_mul_f32_e32 v8, 0xbfb8aa3b, v8
	v_mul_f32_e32 v9, 0xbfb8aa3b, v9
	v_exp_f32_e32 v10, v10
	v_exp_f32_e32 v11, v11
	v_exp_f32_e32 v12, v12
	v_exp_f32_e32 v13, v13
	v_exp_f32_e32 v8, v8
	v_exp_f32_e32 v9, v9
	v_add_f32_e32 v0, 1.0, v0
	v_add_f32_e32 v18, 1.0, v18
	v_add_f32_e32 v19, 1.0, v19
	v_add_f32_e32 v20, 1.0, v20
	v_add_f32_e32 v6, 1.0, v6
	v_add_f32_e32 v7, 1.0, v7
	v_add_f32_e32 v14, 1.0, v14
	v_add_f32_e32 v15, 1.0, v15
	v_add_f32_e32 v16, 1.0, v16
	v_add_f32_e32 v17, 1.0, v17
	v_rcp_f32_e32 v0, v0
	v_rcp_f32_e32 v18, v18
	v_rcp_f32_e32 v19, v19
	v_rcp_f32_e32 v20, v20
	v_rcp_f32_e32 v21, v6
	v_rcp_f32_e32 v26, v7
	v_cvt_pk_bf16_f32 v190, v0, v18
	v_cvt_pk_bf16_f32 v191, v19, v20
	v_add_f32_e32 v10, 1.0, v10
	v_add_f32_e32 v11, 1.0, v11
	v_add_f32_e32 v12, 1.0, v12
	v_add_f32_e32 v13, 1.0, v13
	v_rcp_f32_e32 v14, v14
	v_rcp_f32_e32 v15, v15
	v_rcp_f32_e32 v16, v16
	v_rcp_f32_e32 v17, v17
	v_cvt_pk_bf16_f32 v192, v14, v15
	v_cvt_pk_bf16_f32 v193, v16, v17
	v_add_f32_e32 v8, 1.0, v8
	v_add_f32_e32 v9, 1.0, v9
	v_rcp_f32_e32 v10, v10
	v_rcp_f32_e32 v11, v11
	v_rcp_f32_e32 v12, v12
	v_rcp_f32_e32 v13, v13
	v_cvt_pk_bf16_f32 v194, v10, v11
	v_cvt_pk_bf16_f32 v195, v12, v13
	v_rcp_f32_e32 v8, v8
	v_rcp_f32_e32 v9, v9
	v_cvt_pk_bf16_f32 v196, v21, v26
	v_cvt_pk_bf16_f32 v197, v8, v9
	s_nop 1
	v_permlane16_swap_b32_e32 v190, v192
	v_permlane16_swap_b32_e32 v191, v193
	v_permlane16_swap_b32_e32 v194, v196
	v_permlane16_swap_b32_e32 v195, v197
	global_store_dwordx4 v[22:23], v[190:193], off
	global_store_dwordx4 v[22:23], v[194:197], off offset:256
	s_andn2_b64 vcc, exec, s[8:9]
	s_mov_b64 s[0:1], -1
	s_cbranch_vccz .LBB0_723

;     __device__ __forceinline__ void operator()(const f32x4 (&acc)[2][2][4][2], const pg8::Unit& u, int wr, int wc, int fr, int fq) const {
;     ...
;         const int hd = 4 * u.pn + wc;
;         const bool isA = hd < 12; const int hb = isA ? 0 : hd - 12, t = hb / 12, jj = hb - 12 * t, g = isA ? 0 : (jj >> 2);
;         const int kind = isA ? ((hd >= 8) + (hd >= 10)) : t;
;         const int hs = isA ? (hd & 1) : (jj & 3), H = isA ? 2 : 4;
;         const int idx = isA ? (kind == 0 ? hd : hs) : ((kind == 0 ? 8 : 2) + jj);
;         const int sh = 2 * g, dil = 1 << sh, win = 128 << sh;
;         const size_t so_p = isA ? O_AP : (O_B1P + (g > 0 ? O_B2P - O_B1P : 0) + (g > 1 ? O_B3P - O_B2P : 0));
;         const size_t so_s = isA ? O_AS : (O_B1S + (g > 0 ? O_B2S - O_B1S : 0) + (g > 1 ? O_B3S - O_B2S : 0));
;         const int gi = (kind == 2) ? 4 : ((isA ? 0 : 2) + kind);
;         const size_t boff = WS_QP + (kind > 0 ? WS_KP - WS_QP : 0) + (kind > 1 ? WS_VP - WS_KP : 0); const int nh = kind == 0 ? 20 : 14;
;         f32x4 gv[2][2];
; #pragma unroll
;         for (int bj = 0; bj < 2; ++bj)
; #pragma unroll
;             for (int n = 0; n < 2; ++n) gv[bj][n] = *(const f32x4*)(GT + gi * 64 + 32 * bj + 16 * n + 4 * fq);
; #pragma unroll
;         for (int ai = 0; ai < 2; ++ai)
; #pragma unroll
;             for (int m = 0; m < 4; ++m) { const int row = row0 + ai * 128 + m * 16; const float rs = __builtin_amdgcn_rsqf(ss[row] * (1.f / DM) + EPS);
;                 f32x4 v[2][2]; float s = 0.f;
; #pragma unroll
;                 for (int bj = 0; bj < 2; ++bj)
; #pragma unroll
;                     for (int n = 0; n < 2; ++n) { v[bj][n] = acc[ai][bj][m][n] * rs; s += (v[bj][n][0] * v[bj][n][0] + v[bj][n][1] * v[bj][n][1]) + (v[bj][n][2] * v[bj][n][2] + v[bj][n][3] * v[bj][n][3]); }
;                 s += __shfl_xor(s, 16); s += __shfl_xor(s, 32);
;                 const float inv = (kind < 2) ? __builtin_amdgcn_rsqf(s * (1.f / 64.f) + EPS) : 1.f;
.LBB0_609:
	s_ashr_i32 s5, s7, 2
	s_and_b64 s[52:53], s[0:1], exec
	s_cselect_b32 s5, 0, s5
	s_cselect_b32 s10, s10, s6
	s_and_b32 s3, s3, 3
	s_and_b64 s[6:7], s[0:1], exec
	s_cselect_b32 s25, s87, s3
	s_lshl_b32 s41, s5, 1
	s_cmp_gt_i32 s5, 1
	s_cselect_b32 s6, 0x400000, 0
	s_cselect_b32 s3, 0x2000000, 0
	s_cmp_gt_i32 s5, 0
	s_mov_b32 s5, 0x21a0000
	v_and_b32_e32 v150, 64, v238
	s_cselect_b32 s18, s5, 0x20a0000
	s_mov_b32 s5, 0x41a0000
	v_xor_b32_e32 v0, 16, v238
	v_add_u32_e32 v150, 64, v150
	s_mov_b32 s7, s19
	s_cselect_b32 s5, s5, 0x39a0000
	s_add_i32 s4, s4, s10
	v_cmp_lt_i32_e32 vcc, v0, v150
	s_or_b64 s[6:7], s[18:19], s[6:7]
	s_add_i32 s3, s5, s3
	s_lshl_b32 s4, s4, 6
	v_cndmask_b32_e32 v0, v238, v0, vcc
	s_cmp_lg_u32 s10, 2
	v_lshlrev_b32_e32 v184, 2, v0
	v_xor_b32_e32 v0, 32, v238
	s_cselect_b32 s18, s4, 0x100
	v_cmp_lt_i32_e32 vcc, v0, v150
	v_ashrrev_i32_e32 v167, 31, v166
	v_lshl_add_u64 v[134:135], s[18:19], 2, v[206:207]
	v_cndmask_b32_e32 v0, v238, v0, vcc
	v_lshl_add_u64 v[170:171], v[166:167], 2, s[26:27]
	global_load_dwordx4 v[146:149], v[134:135], off
	global_load_dwordx4 v[142:145], v[134:135], off offset:64
	global_load_dwordx4 v[138:141], v[134:135], off offset:128
	s_nop 0
	global_load_dwordx4 v[134:137], v[134:135], off offset:192
	v_lshlrev_b32_e32 v185, 2, v0
	global_load_dword v194, v[170:171], off
	global_load_dword v195, v[170:171], off offset:64
	global_load_dword v196, v[170:171], off offset:128
	global_load_dword v197, v[170:171], off offset:192
	v_sub_co_u32_e64 v168, s[4:5], s10, 1
	s_xor_b64 s[54:55], s[4:5], -1
	s_lshl_b32 s70, 0x80, s41
	s_and_b64 s[0:1], s[0:1], exec
	s_cselect_b32 s52, 0x2020000, s6
	s_cselect_b32 s53, 0, s7
	s_cselect_b32 s58, 0x35a0000, s3
	s_cselect_b32 s59, 0, 0
	s_and_b64 s[0:1], s[4:5], exec
	s_mov_b32 s0, 0x1e900000
	s_cselect_b32 s43, s0, 0x23900000
	s_cmp_gt_u32 s10, 1
	s_cselect_b32 s51, 0x3800000, 0
	s_and_b64 s[0:1], s[4:5], exec
	s_cselect_b32 s96, 20, 14
	s_cmp_lt_u32 s10, 2
	s_cselect_b64 s[10:11], -1, 0
	s_add_i32 s60, s70, -1
	s_ashr_i32 s3, s70, 31
	s_ashr_i32 s61, s60, 31
	v_ashrrev_i32_e32 v169, 31, v168
	s_mov_b32 s18, s25
	s_ashr_i32 s57, s56, 31
	v_cmp_lt_i32_e32 vcc, s95, v166
	s_mov_b64 s[6:7], 0
	s_waitcnt vmcnt(0)
	v_mov_b32_e32 v0, v194
	v_fmamk_f32 v0, v0, 0x3a800000, v236
	v_rsq_f32_e32 v0, v0
	s_nop 0
	v_pk_mul_f32 v[150:151], v[132:133], v[0:1] op_sel_hi:[1,0]
	v_pk_mul_f32 v[152:153], v[130:131], v[0:1] op_sel_hi:[1,0]
	v_pk_mul_f32 v[154:155], v[150:151], v[150:151]
	v_pk_mul_f32 v[156:157], v[152:153], v[152:153]
	v_pk_mul_f32 v[164:165], v[118:119], v[0:1] op_sel_hi:[1,0]
	v_pk_mov_b32 v[158:159], v[156:157], v[154:155] op_sel:[1,0]
	v_mov_b32_e32 v157, v155
	v_pk_add_f32 v[154:155], v[158:159], v[156:157]
	v_pk_mul_f32 v[156:157], v[126:127], v[0:1] op_sel_hi:[1,0]
	v_pk_add_f32 v[172:173], v[154:155], v[154:155] op_sel_hi:[0,1]
	v_pk_mul_f32 v[154:155], v[128:129], v[0:1] op_sel_hi:[1,0]
	v_pk_mul_f32 v[160:161], v[156:157], v[156:157]
	v_pk_mul_f32 v[158:159], v[154:155], v[154:155]
	s_nop 0
	v_pk_mov_b32 v[162:163], v[160:161], v[158:159] op_sel:[1,0]
	v_mov_b32_e32 v161, v159
	v_pk_add_f32 v[158:159], v[162:163], v[160:161]
	v_pk_mul_f32 v[160:161], v[122:123], v[0:1] op_sel_hi:[1,0]
	v_pk_add_f32 v[174:175], v[158:159], v[158:159] op_sel_hi:[0,1]
	v_pk_mul_f32 v[158:159], v[124:125], v[0:1] op_sel_hi:[1,0]
	v_mul_f32_e32 v162, v160, v160
	v_pk_fma_f32 v[176:177], v[160:161], v[160:161], v[162:163] op_sel_hi:[1,1,0]
	v_mul_f32_e32 v162, v158, v158
	v_pk_fma_f32 v[178:179], v[158:159], v[158:159], v[162:163] op_sel_hi:[1,1,0]
	v_pk_mul_f32 v[162:163], v[120:121], v[0:1] op_sel_hi:[1,0]
	v_mul_f32_e32 v176, v164, v164
	v_mul_f32_e32 v178, v165, v165
	v_mul_f32_e32 v172, v162, v162
	v_mul_f32_e32 v174, v163, v163
	v_pk_add_f32 v[176:177], v[176:177], v[178:179]
	v_pk_add_f32 v[172:173], v[172:173], v[174:175]
	s_nop 0
	v_pk_add_f32 v[172:173], v[176:177], v[172:173]
	s_nop 0
	v_add_f32_e32 v0, v172, v173
	ds_bpermute_b32 v167, v184, v0
	s_waitcnt lgkmcnt(0)
	v_add_f32_e32 v167, v0, v167
	ds_bpermute_b32 v172, v185, v167
	s_and_saveexec_b64 s[0:1], vcc
	s_xor_b64 s[0:1], exec, s[0:1]
	s_cbranch_execz .LBB0_617
	s_cmpk_lt_u32 s24, 0x8080
	s_mov_b64 s[4:5], 0
	s_cbranch_scc0 .LBB0_616
	v_add_u32_e32 v0, 0xffff8000, v166
	s_mov_b64 s[4:5], -1
	s_and_b64 vcc, exec, s[54:55]
	s_cbranch_vccz .LBB0_613
	s_lshl_b64 s[4:5], s[58:59], 2
	s_add_u32 s64, s12, s4
	v_mov_b64_e32 v[174:175], s[60:61]
	s_addc_u32 s65, s13, s5
	v_mad_u64_u32 v[174:175], s[4:5], s70, v0, v[174:175]
	v_mov_b32_e32 v176, v175
	v_mad_u64_u32 v[176:177], s[4:5], s3, v0, v[176:177]
	v_mov_b32_e32 v175, v176
	v_lshl_add_u64 v[174:175], v[174:175], 1, v[168:169]
	v_lshlrev_b64 v[174:175], s50, v[174:175]
	v_lshl_add_u64 v[176:177], v[174:175], 0, s[18:19]
	s_mov_b64 s[4:5], 0

; __device__ __forceinline__ unsigned cvt_pk_bf16(float lo, float hi) { unsigned r; asm volatile("v_cvt_pk_bf16_f32 %0, %1, %2" : "=v"(r) : "v"(lo), "v"(hi)); return r; }
;     __device__ __forceinline__ void operator()(const f32x4 (&acc)[2][2][4][2], const pg8::Unit& u, int wr, int wc, int fr, int fq) const {
;     ...
;                 const float inv = (kind < 2) ? __builtin_amdgcn_rsqf(s * (1.f / 64.f) + EPS) : 1.f;
; #pragma unroll
;                 for (int bj = 0; bj < 2; ++bj)
; #pragma unroll
;                     for (int n = 0; n < 2; ++n) v[bj][n] = v[bj][n] * gv[bj][n] * inv;
;                 if (row < MPR) {
;                     const int b = row >> 11, sq = row & 2047, p = ((sq & (dil - 1)) << (11 - sh)) + (sq >> sh);
;                     bf16* dst = (bf16*)(wsb + boff) + ((size_t)(b * nh + idx) * 2048 + p) * 64;
; #pragma unroll
;                     for (int bj = 0; bj < 2; ++bj)
; #pragma unroll
;                         for (int n = 0; n < 2; ++n) { u32x2 w; w.x = cvt_pk_bf16(v[bj][n][0], v[bj][n][1]); w.y = cvt_pk_bf16(v[bj][n][2], v[bj][n][3]); *(u32x2*)(dst + 32 * bj + 16 * n + 4 * fq) = w; }
.LBB0_617:
	s_or_saveexec_b64 s[62:63], s[0:1]
	s_waitcnt lgkmcnt(0)
	v_add_f32_e32 v167, v167, v172
	v_fmamk_f32 v167, v167, 0x3c800000, v236
	v_rsq_f32_e32 v167, v167
	s_ashr_i32 s4, s24, 11
	v_pk_mul_f32 v[150:151], v[148:149], v[150:151]
	v_pk_mul_f32 v[174:175], v[146:147], v[152:153]
	v_cndmask_b32_e64 v172, 1.0, v167, s[10:11]
	s_mul_i32 s0, s96, s4
	v_pk_mul_f32 v[152:153], v[150:151], v[172:173] op_sel_hi:[1,0]
	v_pk_mul_f32 v[150:151], v[174:175], v[172:173] op_sel_hi:[1,0]
	v_pk_mul_f32 v[154:155], v[144:145], v[154:155]
	v_pk_mul_f32 v[174:175], v[142:143], v[156:157]
	s_add_i32 s0, s56, s0
	v_pk_mul_f32 v[156:157], v[154:155], v[172:173] op_sel_hi:[1,0]
	v_pk_mul_f32 v[154:155], v[174:175], v[172:173] op_sel_hi:[1,0]
	v_pk_mul_f32 v[158:159], v[140:141], v[158:159]
	v_pk_mul_f32 v[174:175], v[138:139], v[160:161]
	s_ashr_i32 s1, s0, 31
	v_pk_mul_f32 v[160:161], v[158:159], v[172:173] op_sel_hi:[1,0]
	v_pk_mul_f32 v[158:159], v[174:175], v[172:173] op_sel_hi:[1,0]
	v_pk_mul_f32 v[162:163], v[136:137], v[162:163]
	v_pk_mul_f32 v[174:175], v[134:135], v[164:165]
	s_sub_i32 s78, 11, s41
	s_sub_i32 s33, 0x800, s70
	v_mov_b32_e32 v0, v168
	s_lshl_b64 s[0:1], s[0:1], 18
	s_mul_hi_i32 s5, s70, s4
	s_mul_i32 s4, s70, s4
	v_pk_mul_f32 v[164:165], v[162:163], v[172:173] op_sel_hi:[1,0]
	v_pk_mul_f32 v[162:163], v[174:175], v[172:173] op_sel_hi:[1,0]
	v_mov_b64_e32 v[178:179], s[64:65]
	v_and_b32_e32 v174, 4, v204
	v_mul_u32_u24_e32 v174, 6, v174
	v_lshl_add_u32 v174, v204, 1, v174
	s_xor_b64 exec, exec, s[62:63]
	s_cbranch_execz .LBB0_621
	s_add_u32 s25, s14, s43
	s_addc_u32 s64, s15, 0
	s_add_u32 s25, s25, s51
	v_and_b32_e32 v167, 0x7cf, v166
	v_lshlrev_b32_e32 v172, s78, v166
	s_addc_u32 s65, s64, 0
	v_and_b32_e32 v172, 0x7fe, v172
	v_lshrrev_b32_e32 v173, s41, v167
	s_add_u32 s64, s25, s0
	s_addc_u32 s65, s65, s1
	v_add_lshl_u32 v172, v172, v173, 7
	v_mov_b32_e32 v173, v1
	v_lshl_add_u64 v[172:173], s[64:65], 0, v[172:173]
	v_mov_b32_e32 v175, v1
	v_lshl_add_u64 v[172:173], v[172:173], 0, v[174:175]
	v_cvt_pk_bf16_f32 v190, v150, v151
	v_cvt_pk_bf16_f32 v191, v152, v153
	v_cvt_pk_bf16_f32 v192, v154, v155
	v_cvt_pk_bf16_f32 v193, v156, v157
	s_nop 1
	v_permlane16_swap_b32_e32 v190, v192
	v_permlane16_swap_b32_e32 v191, v193
	global_store_dwordx4 v[172:173], v[190:193], off
	s_nop 1
	v_cvt_pk_bf16_f32 v190, v158, v159
	v_cvt_pk_bf16_f32 v191, v160, v161
	v_cmp_le_i32_e32 vcc, s33, v167
	v_cvt_pk_bf16_f32 v192, v162, v163
	v_cvt_pk_bf16_f32 v193, v164, v165
	s_and_b64 vcc, s[54:55], vcc
	s_mov_b64 s[68:69], s[6:7]
	s_nop 1
	v_permlane16_swap_b32_e32 v190, v192
	v_permlane16_swap_b32_e32 v191, v193
	global_store_dwordx4 v[172:173], v[190:193], off offset:64
	s_nop 1
	s_and_saveexec_b64 s[66:67], vcc
	s_cbranch_execz .LBB0_620
	v_subrev_u32_e32 v172, s33, v167
	v_mov_b32_e32 v173, v1
	v_lshl_add_u64 v[172:173], s[4:5], 0, v[172:173]
	s_lshl_b64 s[64:65], s[52:53], 2
	v_lshl_add_u64 v[172:173], v[172:173], 1, v[0:1]
	s_add_u32 s64, s12, s64
	v_lshlrev_b64 v[172:173], s50, v[172:173]
	s_addc_u32 s65, s13, s65
	v_lshl_add_u64 v[176:177], v[172:173], 0, s[18:19]
	s_or_b64 s[68:69], s[6:7], exec

;     __device__ __forceinline__ void operator()(const f32x4 (&acc)[2][2][4][2], const pg8::Unit& u, int wr, int wc, int fr, int fq) const {
;     ...
;             for (int m = 0; m < 4; ++m) { const int row = row0 + ai * 128 + m * 16; const float rs = __builtin_amdgcn_rsqf(ss[row] * (1.f / DM) + EPS);
;                 f32x4 v[2][2]; float s = 0.f;
; #pragma unroll
;                 for (int bj = 0; bj < 2; ++bj)
; #pragma unroll
;                     for (int n = 0; n < 2; ++n) { v[bj][n] = acc[ai][bj][m][n] * rs; s += (v[bj][n][0] * v[bj][n][0] + v[bj][n][1] * v[bj][n][1]) + (v[bj][n][2] * v[bj][n][2] + v[bj][n][3] * v[bj][n][3]); }
;                 s += __shfl_xor(s, 16); s += __shfl_xor(s, 32);
.LBB0_623:
	s_or_b64 exec, exec, s[62:63]
	v_or_b32_e32 v176, 16, v166
	v_ashrrev_i32_e32 v177, 31, v176
	v_lshl_add_u64 v[150:151], v[176:177], 2, s[26:27]
	v_cmp_lt_i32_e32 vcc, s95, v176
	s_mov_b64 s[6:7], 0
	v_mov_b32_e32 v150, v195
	v_fmamk_f32 v150, v150, 0x3a800000, v236
	v_rsq_f32_e32 v164, v150
	s_nop 0
	v_pk_mul_f32 v[150:151], v[114:115], v[164:165] op_sel_hi:[1,0]
	v_pk_mul_f32 v[152:153], v[116:117], v[164:165] op_sel_hi:[1,0]
	v_pk_mul_f32 v[156:157], v[150:151], v[150:151]
	v_pk_mul_f32 v[154:155], v[152:153], v[152:153]
	s_nop 0
	v_pk_mov_b32 v[158:159], v[156:157], v[154:155] op_sel:[1,0]
	v_mov_b32_e32 v157, v155
	v_pk_add_f32 v[154:155], v[158:159], v[156:157]
	v_pk_mul_f32 v[156:157], v[112:113], v[164:165] op_sel_hi:[1,0]
	v_pk_add_f32 v[178:179], v[154:155], v[154:155] op_sel_hi:[0,1]
	v_pk_mul_f32 v[154:155], v[110:111], v[164:165] op_sel_hi:[1,0]
	v_pk_mul_f32 v[158:159], v[156:157], v[156:157]
	v_pk_mul_f32 v[160:161], v[154:155], v[154:155]
	s_nop 0
	v_pk_mov_b32 v[162:163], v[160:161], v[158:159] op_sel:[1,0]
	v_mov_b32_e32 v161, v159
	v_pk_add_f32 v[158:159], v[162:163], v[160:161]
	v_pk_mul_f32 v[160:161], v[106:107], v[164:165] op_sel_hi:[1,0]
	v_pk_add_f32 v[180:181], v[158:159], v[158:159] op_sel_hi:[0,1]
	v_pk_mul_f32 v[158:159], v[108:109], v[164:165] op_sel_hi:[1,0]
	v_mul_f32_e32 v162, v160, v160
	v_pk_fma_f32 v[182:183], v[160:161], v[160:161], v[162:163] op_sel_hi:[1,1,0]
	v_mul_f32_e32 v162, v158, v158
	v_pk_fma_f32 v[186:187], v[158:159], v[158:159], v[162:163] op_sel_hi:[1,1,0]
	v_pk_mul_f32 v[162:163], v[104:105], v[164:165] op_sel_hi:[1,0]
	v_pk_mul_f32 v[164:165], v[102:103], v[164:165] op_sel_hi:[1,0]
	v_mul_f32_e32 v178, v162, v162
	v_mul_f32_e32 v182, v164, v164
	v_mul_f32_e32 v186, v165, v165
	v_mul_f32_e32 v180, v163, v163
	v_pk_add_f32 v[182:183], v[182:183], v[186:187]
	v_pk_add_f32 v[178:179], v[178:179], v[180:181]
	s_nop 0
	v_pk_add_f32 v[178:179], v[182:183], v[178:179]
	s_nop 0
	v_add_f32_e32 v167, v178, v179
	ds_bpermute_b32 v173, v184, v167
	s_waitcnt lgkmcnt(0)
	v_add_f32_e32 v167, v167, v173
	ds_bpermute_b32 v173, v185, v167
	s_and_saveexec_b64 s[62:63], vcc
	s_xor_b64 s[62:63], exec, s[62:63]
	s_cbranch_execz .LBB0_631
	s_cmpk_lt_u32 s24, 0x8080
	s_cbranch_scc0 .LBB0_630
	v_add_u32_e32 v175, 0xffff8010, v166
	s_andn2_b64 vcc, exec, s[54:55]
	s_mov_b64 s[6:7], -1
	s_cbranch_vccnz .LBB0_627
	s_lshl_b64 s[6:7], s[58:59], 2
	s_add_u32 s64, s12, s6
	v_mov_b64_e32 v[176:177], s[60:61]
	s_addc_u32 s65, s13, s7
	v_mad_u64_u32 v[176:177], s[6:7], s70, v175, v[176:177]
	v_mov_b32_e32 v178, v177
	v_mad_u64_u32 v[178:179], s[6:7], s3, v175, v[178:179]
	v_mov_b32_e32 v177, v178
	v_lshl_add_u64 v[176:177], v[176:177], 1, v[168:169]
	v_lshlrev_b64 v[176:177], s50, v[176:177]
	v_lshl_add_u64 v[178:179], v[176:177], 0, s[18:19]
	s_mov_b64 s[6:7], 0

; __device__ __forceinline__ unsigned cvt_pk_bf16(float lo, float hi) { unsigned r; asm volatile("v_cvt_pk_bf16_f32 %0, %1, %2" : "=v"(r) : "v"(lo), "v"(hi)); return r; }
;     __device__ __forceinline__ void operator()(const f32x4 (&acc)[2][2][4][2], const pg8::Unit& u, int wr, int wc, int fr, int fq) const {
;     ...
;                 const float inv = (kind < 2) ? __builtin_amdgcn_rsqf(s * (1.f / 64.f) + EPS) : 1.f;
; #pragma unroll
;                 for (int bj = 0; bj < 2; ++bj)
; #pragma unroll
;                     for (int n = 0; n < 2; ++n) v[bj][n] = v[bj][n] * gv[bj][n] * inv;
;                 if (row < MPR) {
;                     const int b = row >> 11, sq = row & 2047, p = ((sq & (dil - 1)) << (11 - sh)) + (sq >> sh);
;                     bf16* dst = (bf16*)(wsb + boff) + ((size_t)(b * nh + idx) * 2048 + p) * 64;
; #pragma unroll
;                     for (int bj = 0; bj < 2; ++bj)
; #pragma unroll
;                         for (int n = 0; n < 2; ++n) { u32x2 w; w.x = cvt_pk_bf16(v[bj][n][0], v[bj][n][1]); w.y = cvt_pk_bf16(v[bj][n][2], v[bj][n][3]); *(u32x2*)(dst + 32 * bj + 16 * n + 4 * fq) = w; }
.LBB0_631:
	s_or_saveexec_b64 s[62:63], s[62:63]
	s_waitcnt lgkmcnt(0)
	v_add_f32_e32 v167, v167, v173
	v_fmamk_f32 v167, v167, 0x3c800000, v236
	v_rsq_f32_e32 v167, v167
	v_pk_mul_f32 v[182:183], v[138:139], v[160:161]
	v_pk_mul_f32 v[158:159], v[140:141], v[158:159]
	v_pk_mul_f32 v[150:151], v[146:147], v[150:151]
	v_cndmask_b32_e64 v180, 1.0, v167, s[10:11]
	v_pk_mul_f32 v[152:153], v[148:149], v[152:153]
	v_pk_mul_f32 v[154:155], v[142:143], v[154:155]
	v_pk_mul_f32 v[156:157], v[144:145], v[156:157]
	v_pk_mul_f32 v[160:161], v[158:159], v[180:181] op_sel_hi:[1,0]
	v_pk_mul_f32 v[158:159], v[182:183], v[180:181] op_sel_hi:[1,0]
	v_pk_mul_f32 v[182:183], v[134:135], v[164:165]
	v_pk_mul_f32 v[162:163], v[136:137], v[162:163]
	v_pk_mul_f32 v[152:153], v[152:153], v[180:181] op_sel_hi:[1,0]
	v_pk_mul_f32 v[150:151], v[150:151], v[180:181] op_sel_hi:[1,0]
	v_pk_mul_f32 v[156:157], v[156:157], v[180:181] op_sel_hi:[1,0]
	v_pk_mul_f32 v[154:155], v[154:155], v[180:181] op_sel_hi:[1,0]
	v_pk_mul_f32 v[164:165], v[162:163], v[180:181] op_sel_hi:[1,0]
	v_pk_mul_f32 v[162:163], v[182:183], v[180:181] op_sel_hi:[1,0]
	v_mov_b64_e32 v[180:181], s[64:65]
	s_xor_b64 exec, exec, s[62:63]
	s_cbranch_execz .LBB0_635
	s_add_u32 s25, s14, s43
	s_addc_u32 s64, s15, 0
	s_add_u32 s25, s25, s51
	v_and_b32_e32 v167, 0x7df, v176
	v_lshlrev_b32_e32 v173, s78, v176
	s_addc_u32 s65, s64, 0
	v_and_b32_e32 v173, 0x7fe, v173
	v_lshrrev_b32_e32 v175, s41, v167
	s_add_u32 s64, s25, s0
	s_addc_u32 s65, s65, s1
	v_add_lshl_u32 v176, v173, v175, 7
	v_mov_b32_e32 v177, v1
	v_lshl_add_u64 v[176:177], s[64:65], 0, v[176:177]
	v_mov_b32_e32 v175, v1
	v_lshl_add_u64 v[176:177], v[176:177], 0, v[174:175]
	v_cvt_pk_bf16_f32 v190, v150, v151
	v_cvt_pk_bf16_f32 v191, v152, v153
	v_cvt_pk_bf16_f32 v192, v154, v155
	v_cvt_pk_bf16_f32 v193, v156, v157
	s_nop 1
	v_permlane16_swap_b32_e32 v190, v192
	v_permlane16_swap_b32_e32 v191, v193
	global_store_dwordx4 v[176:177], v[190:193], off
	s_nop 1
	v_cvt_pk_bf16_f32 v190, v158, v159
	v_cvt_pk_bf16_f32 v191, v160, v161
	v_cmp_le_i32_e32 vcc, s33, v167
	v_cvt_pk_bf16_f32 v192, v162, v163
	v_cvt_pk_bf16_f32 v193, v164, v165
	s_and_b64 vcc, s[54:55], vcc
	s_mov_b64 s[68:69], s[6:7]
	s_nop 1
	v_permlane16_swap_b32_e32 v190, v192
	v_permlane16_swap_b32_e32 v191, v193
	global_store_dwordx4 v[176:177], v[190:193], off offset:64
	s_nop 1
	s_and_saveexec_b64 s[66:67], vcc
	s_cbranch_execz .LBB0_634
	v_subrev_u32_e32 v176, s33, v167
	v_mov_b32_e32 v177, v1
	v_lshl_add_u64 v[176:177], s[4:5], 0, v[176:177]
	s_lshl_b64 s[64:65], s[52:53], 2
	v_lshl_add_u64 v[176:177], v[176:177], 1, v[0:1]
	s_add_u32 s64, s12, s64
	v_lshlrev_b64 v[176:177], s50, v[176:177]
	s_addc_u32 s65, s13, s65
	v_lshl_add_u64 v[178:179], v[176:177], 0, s[18:19]
	s_or_b64 s[68:69], s[6:7], exec

;     __device__ __forceinline__ void operator()(const f32x4 (&acc)[2][2][4][2], const pg8::Unit& u, int wr, int wc, int fr, int fq) const {
;     ...
;             for (int m = 0; m < 4; ++m) { const int row = row0 + ai * 128 + m * 16; const float rs = __builtin_amdgcn_rsqf(ss[row] * (1.f / DM) + EPS);
;                 f32x4 v[2][2]; float s = 0.f;
; #pragma unroll
;                 for (int bj = 0; bj < 2; ++bj)
; #pragma unroll
;                     for (int n = 0; n < 2; ++n) { v[bj][n] = acc[ai][bj][m][n] * rs; s += (v[bj][n][0] * v[bj][n][0] + v[bj][n][1] * v[bj][n][1]) + (v[bj][n][2] * v[bj][n][2] + v[bj][n][3] * v[bj][n][3]); }
;                 s += __shfl_xor(s, 16); s += __shfl_xor(s, 32);
.LBB0_637:
	s_or_b64 exec, exec, s[62:63]
	v_or_b32_e32 v176, 32, v166
	v_ashrrev_i32_e32 v177, 31, v176
	v_lshl_add_u64 v[150:151], v[176:177], 2, s[26:27]
	v_cmp_lt_i32_e32 vcc, s95, v176
	s_mov_b64 s[6:7], 0
	v_mov_b32_e32 v150, v196
	v_fmamk_f32 v150, v150, 0x3a800000, v236
	v_rsq_f32_e32 v164, v150
	s_nop 0
	v_pk_mul_f32 v[150:151], v[98:99], v[164:165] op_sel_hi:[1,0]
	v_pk_mul_f32 v[152:153], v[100:101], v[164:165] op_sel_hi:[1,0]
	v_pk_mul_f32 v[156:157], v[150:151], v[150:151]
	v_pk_mul_f32 v[154:155], v[152:153], v[152:153]
	s_nop 0
	v_pk_mov_b32 v[158:159], v[156:157], v[154:155] op_sel:[1,0]
	v_mov_b32_e32 v157, v155
	v_pk_add_f32 v[154:155], v[158:159], v[156:157]
	v_pk_mul_f32 v[156:157], v[96:97], v[164:165] op_sel_hi:[1,0]
	v_pk_add_f32 v[178:179], v[154:155], v[154:155] op_sel_hi:[0,1]
	v_pk_mul_f32 v[154:155], v[94:95], v[164:165] op_sel_hi:[1,0]
	v_pk_mul_f32 v[158:159], v[156:157], v[156:157]
	v_pk_mul_f32 v[160:161], v[154:155], v[154:155]
	s_nop 0
	v_pk_mov_b32 v[162:163], v[160:161], v[158:159] op_sel:[1,0]
	v_mov_b32_e32 v161, v159
	v_pk_add_f32 v[158:159], v[162:163], v[160:161]
	v_pk_mul_f32 v[160:161], v[90:91], v[164:165] op_sel_hi:[1,0]
	v_pk_add_f32 v[180:181], v[158:159], v[158:159] op_sel_hi:[0,1]
	v_pk_mul_f32 v[158:159], v[92:93], v[164:165] op_sel_hi:[1,0]
	v_mul_f32_e32 v162, v160, v160
	v_pk_fma_f32 v[182:183], v[160:161], v[160:161], v[162:163] op_sel_hi:[1,1,0]
	v_mul_f32_e32 v162, v158, v158
	v_pk_fma_f32 v[186:187], v[158:159], v[158:159], v[162:163] op_sel_hi:[1,1,0]
	v_pk_mul_f32 v[162:163], v[88:89], v[164:165] op_sel_hi:[1,0]
	v_pk_mul_f32 v[164:165], v[86:87], v[164:165] op_sel_hi:[1,0]
	v_mul_f32_e32 v178, v162, v162
	v_mul_f32_e32 v182, v164, v164
	v_mul_f32_e32 v186, v165, v165
	v_mul_f32_e32 v180, v163, v163
	v_pk_add_f32 v[182:183], v[182:183], v[186:187]
	v_pk_add_f32 v[178:179], v[178:179], v[180:181]
	s_nop 0
	v_pk_add_f32 v[178:179], v[182:183], v[178:179]
	s_nop 0
	v_add_f32_e32 v167, v178, v179
	ds_bpermute_b32 v173, v184, v167
	s_waitcnt lgkmcnt(0)
	v_add_f32_e32 v167, v167, v173
	ds_bpermute_b32 v173, v185, v167
	s_and_saveexec_b64 s[62:63], vcc
	s_xor_b64 s[62:63], exec, s[62:63]
	s_cbranch_execz .LBB0_645
	s_cmpk_lt_u32 s24, 0x8080
	s_cbranch_scc0 .LBB0_644
	v_add_u32_e32 v175, 0xffff8020, v166
	s_andn2_b64 vcc, exec, s[54:55]
	s_mov_b64 s[6:7], -1
	s_cbranch_vccnz .LBB0_641
	s_lshl_b64 s[6:7], s[58:59], 2
	s_add_u32 s64, s12, s6
	v_mov_b64_e32 v[176:177], s[60:61]
	s_addc_u32 s65, s13, s7
	v_mad_u64_u32 v[176:177], s[6:7], s70, v175, v[176:177]
	v_mov_b32_e32 v178, v177
	v_mad_u64_u32 v[178:179], s[6:7], s3, v175, v[178:179]
	v_mov_b32_e32 v177, v178
	v_lshl_add_u64 v[176:177], v[176:177], 1, v[168:169]
	v_lshlrev_b64 v[176:177], s50, v[176:177]
	v_lshl_add_u64 v[178:179], v[176:177], 0, s[18:19]
	s_mov_b64 s[6:7], 0

; __device__ __forceinline__ unsigned cvt_pk_bf16(float lo, float hi) { unsigned r; asm volatile("v_cvt_pk_bf16_f32 %0, %1, %2" : "=v"(r) : "v"(lo), "v"(hi)); return r; }
;     __device__ __forceinline__ void operator()(const f32x4 (&acc)[2][2][4][2], const pg8::Unit& u, int wr, int wc, int fr, int fq) const {
;     ...
;                 const float inv = (kind < 2) ? __builtin_amdgcn_rsqf(s * (1.f / 64.f) + EPS) : 1.f;
; #pragma unroll
;                 for (int bj = 0; bj < 2; ++bj)
; #pragma unroll
;                     for (int n = 0; n < 2; ++n) v[bj][n] = v[bj][n] * gv[bj][n] * inv;
;                 if (row < MPR) {
;                     const int b = row >> 11, sq = row & 2047, p = ((sq & (dil - 1)) << (11 - sh)) + (sq >> sh);
;                     bf16* dst = (bf16*)(wsb + boff) + ((size_t)(b * nh + idx) * 2048 + p) * 64;
; #pragma unroll
;                     for (int bj = 0; bj < 2; ++bj)
; #pragma unroll
;                         for (int n = 0; n < 2; ++n) { u32x2 w; w.x = cvt_pk_bf16(v[bj][n][0], v[bj][n][1]); w.y = cvt_pk_bf16(v[bj][n][2], v[bj][n][3]); *(u32x2*)(dst + 32 * bj + 16 * n + 4 * fq) = w; }
.LBB0_645:
	s_or_saveexec_b64 s[62:63], s[62:63]
	s_waitcnt lgkmcnt(0)
	v_add_f32_e32 v167, v167, v173
	v_fmamk_f32 v167, v167, 0x3c800000, v236
	v_rsq_f32_e32 v167, v167
	v_pk_mul_f32 v[182:183], v[138:139], v[160:161]
	v_pk_mul_f32 v[158:159], v[140:141], v[158:159]
	v_pk_mul_f32 v[150:151], v[146:147], v[150:151]
	v_cndmask_b32_e64 v180, 1.0, v167, s[10:11]
	v_pk_mul_f32 v[152:153], v[148:149], v[152:153]
	v_pk_mul_f32 v[154:155], v[142:143], v[154:155]
	v_pk_mul_f32 v[156:157], v[144:145], v[156:157]
	v_pk_mul_f32 v[160:161], v[158:159], v[180:181] op_sel_hi:[1,0]
	v_pk_mul_f32 v[158:159], v[182:183], v[180:181] op_sel_hi:[1,0]
	v_pk_mul_f32 v[182:183], v[134:135], v[164:165]
	v_pk_mul_f32 v[162:163], v[136:137], v[162:163]
	v_pk_mul_f32 v[152:153], v[152:153], v[180:181] op_sel_hi:[1,0]
	v_pk_mul_f32 v[150:151], v[150:151], v[180:181] op_sel_hi:[1,0]
	v_pk_mul_f32 v[156:157], v[156:157], v[180:181] op_sel_hi:[1,0]
	v_pk_mul_f32 v[154:155], v[154:155], v[180:181] op_sel_hi:[1,0]
	v_pk_mul_f32 v[164:165], v[162:163], v[180:181] op_sel_hi:[1,0]
	v_pk_mul_f32 v[162:163], v[182:183], v[180:181] op_sel_hi:[1,0]
	v_mov_b64_e32 v[180:181], s[64:65]
	s_xor_b64 exec, exec, s[62:63]
	s_cbranch_execz .LBB0_649
	s_add_u32 s25, s14, s43
	s_addc_u32 s64, s15, 0
	s_add_u32 s25, s25, s51
	v_and_b32_e32 v167, 0x7ef, v176
	v_lshlrev_b32_e32 v173, s78, v176
	s_addc_u32 s65, s64, 0
	v_and_b32_e32 v173, 0x7fe, v173
	v_lshrrev_b32_e32 v175, s41, v167
	s_add_u32 s64, s25, s0
	s_addc_u32 s65, s65, s1
	v_add_lshl_u32 v176, v173, v175, 7
	v_mov_b32_e32 v177, v1
	v_lshl_add_u64 v[176:177], s[64:65], 0, v[176:177]
	v_mov_b32_e32 v175, v1
	v_lshl_add_u64 v[176:177], v[176:177], 0, v[174:175]
	v_cvt_pk_bf16_f32 v190, v150, v151
	v_cvt_pk_bf16_f32 v191, v152, v153
	v_cvt_pk_bf16_f32 v192, v154, v155
	v_cvt_pk_bf16_f32 v193, v156, v157
	s_nop 1
	v_permlane16_swap_b32_e32 v190, v192
	v_permlane16_swap_b32_e32 v191, v193
	global_store_dwordx4 v[176:177], v[190:193], off
	s_nop 1
	v_cvt_pk_bf16_f32 v190, v158, v159
	v_cvt_pk_bf16_f32 v191, v160, v161
	v_cmp_le_i32_e32 vcc, s33, v167
	v_cvt_pk_bf16_f32 v192, v162, v163
	v_cvt_pk_bf16_f32 v193, v164, v165
	s_and_b64 vcc, s[54:55], vcc
	s_mov_b64 s[68:69], s[6:7]
	s_nop 1
	v_permlane16_swap_b32_e32 v190, v192
	v_permlane16_swap_b32_e32 v191, v193
	global_store_dwordx4 v[176:177], v[190:193], off offset:64
	s_nop 1
	s_and_saveexec_b64 s[66:67], vcc
	s_cbranch_execz .LBB0_648
	v_subrev_u32_e32 v176, s33, v167
	v_mov_b32_e32 v177, v1
	v_lshl_add_u64 v[176:177], s[4:5], 0, v[176:177]
	s_lshl_b64 s[64:65], s[52:53], 2
	v_lshl_add_u64 v[176:177], v[176:177], 1, v[0:1]
	s_add_u32 s64, s12, s64
	v_lshlrev_b64 v[176:177], s50, v[176:177]
	s_addc_u32 s65, s13, s65
	v_lshl_add_u64 v[178:179], v[176:177], 0, s[18:19]
	s_or_b64 s[68:69], s[6:7], exec

;     __device__ __forceinline__ void operator()(const f32x4 (&acc)[2][2][4][2], const pg8::Unit& u, int wr, int wc, int fr, int fq) const {
;     ...
;             for (int m = 0; m < 4; ++m) { const int row = row0 + ai * 128 + m * 16; const float rs = __builtin_amdgcn_rsqf(ss[row] * (1.f / DM) + EPS);
;                 f32x4 v[2][2]; float s = 0.f;
; #pragma unroll
;                 for (int bj = 0; bj < 2; ++bj)
; #pragma unroll
;                     for (int n = 0; n < 2; ++n) { v[bj][n] = acc[ai][bj][m][n] * rs; s += (v[bj][n][0] * v[bj][n][0] + v[bj][n][1] * v[bj][n][1]) + (v[bj][n][2] * v[bj][n][2] + v[bj][n][3] * v[bj][n][3]); }
;                 s += __shfl_xor(s, 16); s += __shfl_xor(s, 32);
.LBB0_651:
	s_or_b64 exec, exec, s[62:63]
	v_or_b32_e32 v176, 48, v166
	v_ashrrev_i32_e32 v177, 31, v176
	v_lshl_add_u64 v[150:151], v[176:177], 2, s[26:27]
	v_cmp_lt_i32_e32 vcc, s95, v176
	s_mov_b64 s[6:7], 0
	v_mov_b32_e32 v150, v197
	v_fmamk_f32 v150, v150, 0x3a800000, v236
	v_rsq_f32_e32 v164, v150
	s_nop 0
	v_pk_mul_f32 v[150:151], v[82:83], v[164:165] op_sel_hi:[1,0]
	v_pk_mul_f32 v[152:153], v[84:85], v[164:165] op_sel_hi:[1,0]
	v_pk_mul_f32 v[156:157], v[150:151], v[150:151]
	v_pk_mul_f32 v[154:155], v[152:153], v[152:153]
	s_nop 0
	v_pk_mov_b32 v[158:159], v[156:157], v[154:155] op_sel:[1,0]
	v_mov_b32_e32 v157, v155
	v_pk_add_f32 v[154:155], v[158:159], v[156:157]
	v_pk_mul_f32 v[156:157], v[80:81], v[164:165] op_sel_hi:[1,0]
	v_pk_add_f32 v[178:179], v[154:155], v[154:155] op_sel_hi:[0,1]
	v_pk_mul_f32 v[154:155], v[78:79], v[164:165] op_sel_hi:[1,0]
	v_pk_mul_f32 v[158:159], v[156:157], v[156:157]
	v_pk_mul_f32 v[160:161], v[154:155], v[154:155]
	s_nop 0
	v_pk_mov_b32 v[162:163], v[160:161], v[158:159] op_sel:[1,0]
	v_mov_b32_e32 v161, v159
	v_pk_add_f32 v[158:159], v[162:163], v[160:161]
	v_pk_mul_f32 v[160:161], v[74:75], v[164:165] op_sel_hi:[1,0]
	v_pk_add_f32 v[180:181], v[158:159], v[158:159] op_sel_hi:[0,1]
	v_pk_mul_f32 v[158:159], v[76:77], v[164:165] op_sel_hi:[1,0]
	v_mul_f32_e32 v162, v160, v160
	v_pk_fma_f32 v[182:183], v[160:161], v[160:161], v[162:163] op_sel_hi:[1,1,0]
	v_mul_f32_e32 v162, v158, v158
	v_pk_fma_f32 v[186:187], v[158:159], v[158:159], v[162:163] op_sel_hi:[1,1,0]
	v_pk_mul_f32 v[162:163], v[72:73], v[164:165] op_sel_hi:[1,0]
	v_pk_mul_f32 v[164:165], v[70:71], v[164:165] op_sel_hi:[1,0]
	v_mul_f32_e32 v178, v162, v162
	v_mul_f32_e32 v182, v164, v164
	v_mul_f32_e32 v186, v165, v165
	v_mul_f32_e32 v180, v163, v163
	v_pk_add_f32 v[182:183], v[182:183], v[186:187]
	v_pk_add_f32 v[178:179], v[178:179], v[180:181]
	s_nop 0
	v_pk_add_f32 v[178:179], v[182:183], v[178:179]
	s_nop 0
	v_add_f32_e32 v167, v178, v179
	ds_bpermute_b32 v173, v184, v167
	s_waitcnt lgkmcnt(0)
	v_add_f32_e32 v167, v167, v173
	ds_bpermute_b32 v173, v185, v167
	s_and_saveexec_b64 s[62:63], vcc
	s_xor_b64 s[62:63], exec, s[62:63]
	s_cbranch_execz .LBB0_659
	s_cmpk_lt_u32 s24, 0x8080
	s_cbranch_scc0 .LBB0_658
	v_add_u32_e32 v175, 0xffff8030, v166
	s_andn2_b64 vcc, exec, s[54:55]
	s_mov_b64 s[6:7], -1
	s_cbranch_vccnz .LBB0_655
	s_lshl_b64 s[6:7], s[58:59], 2
	s_add_u32 s64, s12, s6
	v_mov_b64_e32 v[176:177], s[60:61]
	s_addc_u32 s65, s13, s7
	v_mad_u64_u32 v[176:177], s[6:7], s70, v175, v[176:177]
	v_mov_b32_e32 v178, v177
	v_mad_u64_u32 v[178:179], s[6:7], s3, v175, v[178:179]
	v_mov_b32_e32 v177, v178
	v_lshl_add_u64 v[176:177], v[176:177], 1, v[168:169]
	v_lshlrev_b64 v[176:177], s50, v[176:177]
	v_lshl_add_u64 v[178:179], v[176:177], 0, s[18:19]
	s_mov_b64 s[6:7], 0

; __device__ __forceinline__ unsigned cvt_pk_bf16(float lo, float hi) { unsigned r; asm volatile("v_cvt_pk_bf16_f32 %0, %1, %2" : "=v"(r) : "v"(lo), "v"(hi)); return r; }
;     __device__ __forceinline__ void operator()(const f32x4 (&acc)[2][2][4][2], const pg8::Unit& u, int wr, int wc, int fr, int fq) const {
;     ...
;                 const float inv = (kind < 2) ? __builtin_amdgcn_rsqf(s * (1.f / 64.f) + EPS) : 1.f;
; #pragma unroll
;                 for (int bj = 0; bj < 2; ++bj)
; #pragma unroll
;                     for (int n = 0; n < 2; ++n) v[bj][n] = v[bj][n] * gv[bj][n] * inv;
;                 if (row < MPR) {
;                     const int b = row >> 11, sq = row & 2047, p = ((sq & (dil - 1)) << (11 - sh)) + (sq >> sh);
;                     bf16* dst = (bf16*)(wsb + boff) + ((size_t)(b * nh + idx) * 2048 + p) * 64;
; #pragma unroll
;                     for (int bj = 0; bj < 2; ++bj)
; #pragma unroll
;                         for (int n = 0; n < 2; ++n) { u32x2 w; w.x = cvt_pk_bf16(v[bj][n][0], v[bj][n][1]); w.y = cvt_pk_bf16(v[bj][n][2], v[bj][n][3]); *(u32x2*)(dst + 32 * bj + 16 * n + 4 * fq) = w; }
.LBB0_659:
	s_or_saveexec_b64 s[62:63], s[62:63]
	s_waitcnt lgkmcnt(0)
	v_add_f32_e32 v167, v167, v173
	v_fmamk_f32 v167, v167, 0x3c800000, v236
	v_rsq_f32_e32 v167, v167
	v_pk_mul_f32 v[182:183], v[138:139], v[160:161]
	v_pk_mul_f32 v[158:159], v[140:141], v[158:159]
	v_pk_mul_f32 v[150:151], v[146:147], v[150:151]
	v_cndmask_b32_e64 v180, 1.0, v167, s[10:11]
	v_pk_mul_f32 v[152:153], v[148:149], v[152:153]
	v_pk_mul_f32 v[154:155], v[142:143], v[154:155]
	v_pk_mul_f32 v[156:157], v[144:145], v[156:157]
	v_pk_mul_f32 v[160:161], v[158:159], v[180:181] op_sel_hi:[1,0]
	v_pk_mul_f32 v[158:159], v[182:183], v[180:181] op_sel_hi:[1,0]
	v_pk_mul_f32 v[182:183], v[134:135], v[164:165]
	v_pk_mul_f32 v[162:163], v[136:137], v[162:163]
	v_pk_mul_f32 v[152:153], v[152:153], v[180:181] op_sel_hi:[1,0]
	v_pk_mul_f32 v[150:151], v[150:151], v[180:181] op_sel_hi:[1,0]
	v_pk_mul_f32 v[156:157], v[156:157], v[180:181] op_sel_hi:[1,0]
	v_pk_mul_f32 v[154:155], v[154:155], v[180:181] op_sel_hi:[1,0]
	v_pk_mul_f32 v[164:165], v[162:163], v[180:181] op_sel_hi:[1,0]
	v_pk_mul_f32 v[162:163], v[182:183], v[180:181] op_sel_hi:[1,0]
	v_mov_b64_e32 v[180:181], s[64:65]
	s_xor_b64 exec, exec, s[62:63]
	s_cbranch_execz .LBB0_663
	s_add_u32 s24, s14, s43
	s_addc_u32 s25, s15, 0
	s_add_u32 s24, s24, s51
	v_and_b32_e32 v167, 0x7ff, v176
	v_lshlrev_b32_e32 v173, s78, v176
	s_addc_u32 s25, s25, 0
	v_and_b32_e32 v173, 0x7fe, v173
	v_lshrrev_b32_e32 v175, s41, v167
	s_add_u32 s0, s24, s0
	s_addc_u32 s1, s25, s1
	v_add_lshl_u32 v176, v173, v175, 7
	v_mov_b32_e32 v177, v1
	v_lshl_add_u64 v[176:177], s[0:1], 0, v[176:177]
	v_mov_b32_e32 v175, v1
	v_lshl_add_u64 v[176:177], v[176:177], 0, v[174:175]
	v_cvt_pk_bf16_f32 v190, v150, v151
	v_cvt_pk_bf16_f32 v191, v152, v153
	v_cvt_pk_bf16_f32 v192, v154, v155
	v_cvt_pk_bf16_f32 v193, v156, v157
	s_nop 1
	v_permlane16_swap_b32_e32 v190, v192
	v_permlane16_swap_b32_e32 v191, v193
	global_store_dwordx4 v[176:177], v[190:193], off
	s_nop 1
	v_cvt_pk_bf16_f32 v190, v158, v159
	v_cvt_pk_bf16_f32 v191, v160, v161
	v_cmp_le_i32_e32 vcc, s33, v167
	v_cvt_pk_bf16_f32 v192, v162, v163
	v_cvt_pk_bf16_f32 v193, v164, v165
	s_and_b64 s[24:25], s[54:55], vcc
	s_mov_b64 s[66:67], s[6:7]
	s_nop 1
	v_permlane16_swap_b32_e32 v190, v192
	v_permlane16_swap_b32_e32 v191, v193
	global_store_dwordx4 v[176:177], v[190:193], off offset:64
	s_nop 1
	s_and_saveexec_b64 s[64:65], s[24:25]
	s_cbranch_execz .LBB0_662
	v_subrev_u32_e32 v176, s33, v167
	v_mov_b32_e32 v177, v1
	v_lshl_add_u64 v[176:177], s[4:5], 0, v[176:177]
	s_lshl_b64 s[0:1], s[52:53], 2
	v_lshl_add_u64 v[176:177], v[176:177], 1, v[0:1]
	s_add_u32 s0, s12, s0
	v_lshlrev_b64 v[176:177], s50, v[176:177]
	s_addc_u32 s1, s13, s1
	v_lshl_add_u64 v[178:179], v[176:177], 0, s[18:19]
	s_or_b64 s[66:67], s[6:7], exec

;     __device__ __forceinline__ void operator()(const f32x4 (&acc)[2][2][4][2], const pg8::Unit& u, int wr, int wc, int fr, int fq) const {
;     ...
;             for (int m = 0; m < 4; ++m) { const int row = row0 + ai * 128 + m * 16; const float rs = __builtin_amdgcn_rsqf(ss[row] * (1.f / DM) + EPS);
;                 f32x4 v[2][2]; float s = 0.f;
; #pragma unroll
;                 for (int bj = 0; bj < 2; ++bj)
; #pragma unroll
;                     for (int n = 0; n < 2; ++n) { v[bj][n] = acc[ai][bj][m][n] * rs; s += (v[bj][n][0] * v[bj][n][0] + v[bj][n][1] * v[bj][n][1]) + (v[bj][n][2] * v[bj][n][2] + v[bj][n][3] * v[bj][n][3]); }
;                 s += __shfl_xor(s, 16); s += __shfl_xor(s, 32);
.LBB0_665:
	s_or_b64 exec, exec, s[0:1]
	global_load_dword v194, v[170:171], off offset:512
	global_load_dword v195, v[170:171], off offset:576
	global_load_dword v196, v[170:171], off offset:640
	global_load_dword v197, v[170:171], off offset:704
	s_movk_i32 s0, 0x7f7f
	v_add_u32_e32 v167, 0x80, v166
	v_cmp_lt_i32_e32 vcc, s0, v166
	s_mov_b64 s[0:1], 0
	s_waitcnt vmcnt(0)
	v_mov_b32_e32 v150, v194
	v_fmamk_f32 v150, v150, 0x3a800000, v236
	v_rsq_f32_e32 v164, v150
	s_nop 0
	v_pk_mul_f32 v[150:151], v[66:67], v[164:165] op_sel_hi:[1,0]
	v_pk_mul_f32 v[152:153], v[68:69], v[164:165] op_sel_hi:[1,0]
	v_pk_mul_f32 v[156:157], v[150:151], v[150:151]
	v_pk_mul_f32 v[154:155], v[152:153], v[152:153]
	s_nop 0
	v_pk_mov_b32 v[158:159], v[156:157], v[154:155] op_sel:[1,0]
	v_mov_b32_e32 v157, v155
	v_pk_add_f32 v[154:155], v[158:159], v[156:157]
	v_pk_mul_f32 v[156:157], v[64:65], v[164:165] op_sel_hi:[1,0]
	v_pk_add_f32 v[176:177], v[154:155], v[154:155] op_sel_hi:[0,1]
	v_pk_mul_f32 v[154:155], v[62:63], v[164:165] op_sel_hi:[1,0]
	v_pk_mul_f32 v[158:159], v[156:157], v[156:157]
	v_pk_mul_f32 v[160:161], v[154:155], v[154:155]
	s_nop 0
	v_pk_mov_b32 v[162:163], v[160:161], v[158:159] op_sel:[1,0]
	v_mov_b32_e32 v161, v159
	v_pk_add_f32 v[158:159], v[162:163], v[160:161]
	v_pk_mul_f32 v[160:161], v[58:59], v[164:165] op_sel_hi:[1,0]
	v_pk_add_f32 v[178:179], v[158:159], v[158:159] op_sel_hi:[0,1]
	v_pk_mul_f32 v[158:159], v[60:61], v[164:165] op_sel_hi:[1,0]
	v_mul_f32_e32 v162, v160, v160
	v_pk_fma_f32 v[180:181], v[160:161], v[160:161], v[162:163] op_sel_hi:[1,1,0]
	v_mul_f32_e32 v162, v158, v158
	v_pk_fma_f32 v[182:183], v[158:159], v[158:159], v[162:163] op_sel_hi:[1,1,0]
	v_pk_mul_f32 v[162:163], v[56:57], v[164:165] op_sel_hi:[1,0]
	v_pk_mul_f32 v[164:165], v[54:55], v[164:165] op_sel_hi:[1,0]
	v_mul_f32_e32 v176, v162, v162
	v_mul_f32_e32 v180, v164, v164
	v_mul_f32_e32 v182, v165, v165
	v_mul_f32_e32 v178, v163, v163
	v_pk_add_f32 v[180:181], v[180:181], v[182:183]
	v_pk_add_f32 v[176:177], v[176:177], v[178:179]
	s_nop 0
	v_pk_add_f32 v[176:177], v[180:181], v[176:177]
	s_nop 0
	v_add_f32_e32 v173, v176, v177
	ds_bpermute_b32 v175, v184, v173
	s_waitcnt lgkmcnt(0)
	v_add_f32_e32 v173, v173, v175
	ds_bpermute_b32 v175, v185, v173
	s_and_saveexec_b64 s[4:5], vcc
	s_xor_b64 s[4:5], exec, s[4:5]
	s_cbranch_execz .LBB0_673
	s_mov_b32 s0, 0x8080
	v_cmp_gt_u32_e32 vcc, s0, v167
	s_mov_b64 s[62:63], 0
	s_and_saveexec_b64 s[0:1], vcc
	s_cbranch_execz .LBB0_672
	v_add_u32_e32 v176, 0xffff8080, v166
	s_andn2_b64 vcc, exec, s[54:55]
	s_mov_b64 s[62:63], -1
	s_cbranch_vccnz .LBB0_669
	v_mov_b64_e32 v[178:179], s[60:61]
	v_mad_u64_u32 v[178:179], s[24:25], s70, v176, v[178:179]
	v_mov_b32_e32 v180, v179
	v_mad_u64_u32 v[180:181], s[24:25], s3, v176, v[180:181]
	v_mov_b32_e32 v179, v180
	s_lshl_b64 s[6:7], s[58:59], 2
	v_lshl_add_u64 v[178:179], v[178:179], 1, v[168:169]
	s_add_u32 s6, s12, s6
	v_lshlrev_b64 v[178:179], s50, v[178:179]
	s_addc_u32 s7, s13, s7
	v_lshl_add_u64 v[180:181], v[178:179], 0, s[18:19]
	s_mov_b64 s[62:63], 0

; __device__ __forceinline__ unsigned cvt_pk_bf16(float lo, float hi) { unsigned r; asm volatile("v_cvt_pk_bf16_f32 %0, %1, %2" : "=v"(r) : "v"(lo), "v"(hi)); return r; }
;     __device__ __forceinline__ void operator()(const f32x4 (&acc)[2][2][4][2], const pg8::Unit& u, int wr, int wc, int fr, int fq) const {
;     ...
;                 const float inv = (kind < 2) ? __builtin_amdgcn_rsqf(s * (1.f / 64.f) + EPS) : 1.f;
; #pragma unroll
;                 for (int bj = 0; bj < 2; ++bj)
; #pragma unroll
;                     for (int n = 0; n < 2; ++n) v[bj][n] = v[bj][n] * gv[bj][n] * inv;
;                 if (row < MPR) {
;                     const int b = row >> 11, sq = row & 2047, p = ((sq & (dil - 1)) << (11 - sh)) + (sq >> sh);
;                     bf16* dst = (bf16*)(wsb + boff) + ((size_t)(b * nh + idx) * 2048 + p) * 64;
; #pragma unroll
;                     for (int bj = 0; bj < 2; ++bj)
; #pragma unroll
;                         for (int n = 0; n < 2; ++n) { u32x2 w; w.x = cvt_pk_bf16(v[bj][n][0], v[bj][n][1]); w.y = cvt_pk_bf16(v[bj][n][2], v[bj][n][3]); *(u32x2*)(dst + 32 * bj + 16 * n + 4 * fq) = w; }
.LBB0_673:
	s_or_saveexec_b64 s[4:5], s[4:5]
	s_waitcnt lgkmcnt(0)
	v_add_f32_e32 v173, v173, v175
	v_fmamk_f32 v173, v173, 0x3c800000, v236
	v_rsq_f32_e32 v173, v173
	v_ashrrev_i32_e32 v182, 11, v167
	v_mov_b32_e32 v176, s56
	v_mad_i32_i24 v176, s96, v182, v176
	v_ashrrev_i32_e32 v177, 31, v176
	v_lshlrev_b64 v[178:179], 18, v[176:177]
	v_mad_i64_i32 v[176:177], s[24:25], s70, v182, 0
	v_cndmask_b32_e64 v182, 1.0, v173, s[10:11]
	v_pk_mul_f32 v[186:187], v[138:139], v[160:161]
	v_pk_mul_f32 v[158:159], v[140:141], v[158:159]
	v_pk_mul_f32 v[150:151], v[146:147], v[150:151]
	v_pk_mul_f32 v[152:153], v[148:149], v[152:153]
	v_pk_mul_f32 v[154:155], v[142:143], v[154:155]
	v_pk_mul_f32 v[156:157], v[144:145], v[156:157]
	v_pk_mul_f32 v[160:161], v[158:159], v[182:183] op_sel_hi:[1,0]
	v_pk_mul_f32 v[158:159], v[186:187], v[182:183] op_sel_hi:[1,0]
	v_pk_mul_f32 v[186:187], v[134:135], v[164:165]
	v_pk_mul_f32 v[162:163], v[136:137], v[162:163]
	v_pk_mul_f32 v[152:153], v[152:153], v[182:183] op_sel_hi:[1,0]
	v_pk_mul_f32 v[150:151], v[150:151], v[182:183] op_sel_hi:[1,0]
	v_pk_mul_f32 v[156:157], v[156:157], v[182:183] op_sel_hi:[1,0]
	v_pk_mul_f32 v[154:155], v[154:155], v[182:183] op_sel_hi:[1,0]
	v_pk_mul_f32 v[164:165], v[162:163], v[182:183] op_sel_hi:[1,0]
	v_pk_mul_f32 v[162:163], v[186:187], v[182:183] op_sel_hi:[1,0]
	v_mov_b64_e32 v[182:183], s[6:7]
	s_xor_b64 exec, exec, s[4:5]
	s_cbranch_execz .LBB0_677
	s_add_u32 s6, s14, s43
	s_addc_u32 s7, s15, 0
	v_and_b32_e32 v173, 0x7cf, v167
	v_lshlrev_b32_e32 v167, s78, v167
	s_add_u32 s6, s6, s51
	v_and_b32_e32 v167, 0x7fe, v167
	v_lshrrev_b32_e32 v175, s41, v173
	s_addc_u32 s7, s7, 0
	v_lshl_add_u64 v[180:181], s[6:7], 0, v[178:179]
	v_add_lshl_u32 v182, v167, v175, 7
	v_mov_b32_e32 v183, v1
	v_lshl_add_u64 v[180:181], v[180:181], 0, v[182:183]
	v_mov_b32_e32 v175, v1
	v_lshl_add_u64 v[180:181], v[180:181], 0, v[174:175]
	v_cvt_pk_bf16_f32 v190, v150, v151
	v_cvt_pk_bf16_f32 v191, v152, v153
	v_cvt_pk_bf16_f32 v192, v154, v155
	v_cvt_pk_bf16_f32 v193, v156, v157
	v_cmp_le_i32_e32 vcc, s33, v173
	s_nop 1
	v_permlane16_swap_b32_e32 v190, v192
	v_permlane16_swap_b32_e32 v191, v193
	global_store_dwordx4 v[180:181], v[190:193], off
	s_nop 1
	v_cvt_pk_bf16_f32 v190, v158, v159
	v_cvt_pk_bf16_f32 v191, v160, v161
	s_and_b64 s[24:25], s[54:55], vcc
	s_mov_b64 s[64:65], s[0:1]
	v_cvt_pk_bf16_f32 v192, v162, v163
	v_cvt_pk_bf16_f32 v193, v164, v165
	s_nop 1
	v_permlane16_swap_b32_e32 v190, v192
	v_permlane16_swap_b32_e32 v191, v193
	global_store_dwordx4 v[180:181], v[190:193], off offset:64
	s_nop 1
	s_and_saveexec_b64 s[62:63], s[24:25]
	s_cbranch_execz .LBB0_676
	v_subrev_u32_e32 v180, s33, v173
	v_mov_b32_e32 v181, v1
	v_lshl_add_u64 v[180:181], v[176:177], 0, v[180:181]
	s_lshl_b64 s[6:7], s[52:53], 2
	v_lshl_add_u64 v[180:181], v[180:181], 1, v[0:1]
	s_add_u32 s6, s12, s6
	v_lshlrev_b64 v[180:181], s50, v[180:181]
	s_addc_u32 s7, s13, s7
	v_lshl_add_u64 v[180:181], v[180:181], 0, s[18:19]
	s_or_b64 s[64:65], s[0:1], exec

;     __device__ __forceinline__ void operator()(const f32x4 (&acc)[2][2][4][2], const pg8::Unit& u, int wr, int wc, int fr, int fq) const {
;     ...
;             for (int m = 0; m < 4; ++m) { const int row = row0 + ai * 128 + m * 16; const float rs = __builtin_amdgcn_rsqf(ss[row] * (1.f / DM) + EPS);
;                 f32x4 v[2][2]; float s = 0.f;
; #pragma unroll
;                 for (int bj = 0; bj < 2; ++bj)
; #pragma unroll
;                     for (int n = 0; n < 2; ++n) { v[bj][n] = acc[ai][bj][m][n] * rs; s += (v[bj][n][0] * v[bj][n][0] + v[bj][n][1] * v[bj][n][1]) + (v[bj][n][2] * v[bj][n][2] + v[bj][n][3] * v[bj][n][3]); }
;                 s += __shfl_xor(s, 16); s += __shfl_xor(s, 32);
.LBB0_679:
	s_or_b64 exec, exec, s[4:5]
	s_movk_i32 s0, 0x7f6f
	v_add_u32_e32 v167, 0x90, v166
	v_cmp_lt_i32_e32 vcc, s0, v166
	s_mov_b64 s[0:1], 0
	v_mov_b32_e32 v150, v195
	v_fmamk_f32 v150, v150, 0x3a800000, v236
	v_rsq_f32_e32 v164, v150
	s_nop 0
	v_pk_mul_f32 v[150:151], v[50:51], v[164:165] op_sel_hi:[1,0]
	v_pk_mul_f32 v[152:153], v[52:53], v[164:165] op_sel_hi:[1,0]
	v_pk_mul_f32 v[156:157], v[150:151], v[150:151]
	v_pk_mul_f32 v[154:155], v[152:153], v[152:153]
	s_nop 0
	v_pk_mov_b32 v[158:159], v[156:157], v[154:155] op_sel:[1,0]
	v_mov_b32_e32 v157, v155
	v_pk_add_f32 v[154:155], v[158:159], v[156:157]
	v_pk_mul_f32 v[156:157], v[48:49], v[164:165] op_sel_hi:[1,0]
	v_pk_add_f32 v[180:181], v[154:155], v[154:155] op_sel_hi:[0,1]
	v_pk_mul_f32 v[154:155], v[46:47], v[164:165] op_sel_hi:[1,0]
	v_pk_mul_f32 v[158:159], v[156:157], v[156:157]
	v_pk_mul_f32 v[160:161], v[154:155], v[154:155]
	s_nop 0
	v_pk_mov_b32 v[162:163], v[160:161], v[158:159] op_sel:[1,0]
	v_mov_b32_e32 v161, v159
	v_pk_add_f32 v[158:159], v[162:163], v[160:161]
	v_pk_mul_f32 v[160:161], v[42:43], v[164:165] op_sel_hi:[1,0]
	v_pk_add_f32 v[182:183], v[158:159], v[158:159] op_sel_hi:[0,1]
	v_pk_mul_f32 v[158:159], v[44:45], v[164:165] op_sel_hi:[1,0]
	v_mul_f32_e32 v162, v160, v160
	v_pk_fma_f32 v[186:187], v[160:161], v[160:161], v[162:163] op_sel_hi:[1,1,0]
	v_mul_f32_e32 v162, v158, v158
	v_pk_fma_f32 v[188:189], v[158:159], v[158:159], v[162:163] op_sel_hi:[1,1,0]
	v_pk_mul_f32 v[162:163], v[40:41], v[164:165] op_sel_hi:[1,0]
	v_pk_mul_f32 v[164:165], v[38:39], v[164:165] op_sel_hi:[1,0]
	v_mul_f32_e32 v180, v162, v162
	v_mul_f32_e32 v186, v164, v164
	v_mul_f32_e32 v188, v165, v165
	v_mul_f32_e32 v182, v163, v163
	v_pk_add_f32 v[186:187], v[186:187], v[188:189]
	v_pk_add_f32 v[180:181], v[180:181], v[182:183]
	s_nop 0
	v_pk_add_f32 v[180:181], v[186:187], v[180:181]
	s_nop 0
	v_add_f32_e32 v173, v180, v181
	ds_bpermute_b32 v175, v184, v173
	s_waitcnt lgkmcnt(0)
	v_add_f32_e32 v173, v173, v175
	ds_bpermute_b32 v175, v185, v173
	s_and_saveexec_b64 s[4:5], vcc
	s_xor_b64 s[4:5], exec, s[4:5]
	s_cbranch_execz .LBB0_687
	s_mov_b32 s0, 0x8080
	v_cmp_gt_u32_e32 vcc, s0, v167
	s_mov_b64 s[62:63], 0
	s_and_saveexec_b64 s[0:1], vcc
	s_cbranch_execz .LBB0_686
	v_add_u32_e32 v167, 0xffff8090, v166
	s_andn2_b64 vcc, exec, s[54:55]
	s_mov_b64 s[62:63], -1
	s_cbranch_vccnz .LBB0_683
	v_mov_b64_e32 v[180:181], s[60:61]
	v_mad_u64_u32 v[180:181], s[24:25], s70, v167, v[180:181]
	v_mov_b32_e32 v182, v181
	v_mad_u64_u32 v[182:183], s[24:25], s3, v167, v[182:183]
	v_mov_b32_e32 v181, v182
	s_lshl_b64 s[6:7], s[58:59], 2
	v_lshl_add_u64 v[180:181], v[180:181], 1, v[168:169]
	s_add_u32 s6, s12, s6
	v_lshlrev_b64 v[180:181], s50, v[180:181]
	s_addc_u32 s7, s13, s7
	v_lshl_add_u64 v[180:181], v[180:181], 0, s[18:19]
	s_mov_b64 s[62:63], 0

; __device__ __forceinline__ unsigned cvt_pk_bf16(float lo, float hi) { unsigned r; asm volatile("v_cvt_pk_bf16_f32 %0, %1, %2" : "=v"(r) : "v"(lo), "v"(hi)); return r; }
;     __device__ __forceinline__ void operator()(const f32x4 (&acc)[2][2][4][2], const pg8::Unit& u, int wr, int wc, int fr, int fq) const {
;     ...
;                 const float inv = (kind < 2) ? __builtin_amdgcn_rsqf(s * (1.f / 64.f) + EPS) : 1.f;
; #pragma unroll
;                 for (int bj = 0; bj < 2; ++bj)
; #pragma unroll
;                     for (int n = 0; n < 2; ++n) v[bj][n] = v[bj][n] * gv[bj][n] * inv;
;                 if (row < MPR) {
;                     const int b = row >> 11, sq = row & 2047, p = ((sq & (dil - 1)) << (11 - sh)) + (sq >> sh);
;                     bf16* dst = (bf16*)(wsb + boff) + ((size_t)(b * nh + idx) * 2048 + p) * 64;
; #pragma unroll
;                     for (int bj = 0; bj < 2; ++bj)
; #pragma unroll
;                         for (int n = 0; n < 2; ++n) { u32x2 w; w.x = cvt_pk_bf16(v[bj][n][0], v[bj][n][1]); w.y = cvt_pk_bf16(v[bj][n][2], v[bj][n][3]); *(u32x2*)(dst + 32 * bj + 16 * n + 4 * fq) = w; }
.LBB0_687:
	s_or_saveexec_b64 s[4:5], s[4:5]
	s_waitcnt lgkmcnt(0)
	v_add_f32_e32 v173, v173, v175
	v_fmamk_f32 v173, v173, 0x3c800000, v236
	v_rsq_f32_e32 v173, v173
	v_pk_mul_f32 v[186:187], v[138:139], v[160:161]
	v_pk_mul_f32 v[158:159], v[140:141], v[158:159]
	v_pk_mul_f32 v[150:151], v[146:147], v[150:151]
	v_cndmask_b32_e64 v182, 1.0, v173, s[10:11]
	v_pk_mul_f32 v[152:153], v[148:149], v[152:153]
	v_pk_mul_f32 v[154:155], v[142:143], v[154:155]
	v_pk_mul_f32 v[156:157], v[144:145], v[156:157]
	v_pk_mul_f32 v[160:161], v[158:159], v[182:183] op_sel_hi:[1,0]
	v_pk_mul_f32 v[158:159], v[186:187], v[182:183] op_sel_hi:[1,0]
	v_pk_mul_f32 v[186:187], v[134:135], v[164:165]
	v_pk_mul_f32 v[162:163], v[136:137], v[162:163]
	v_pk_mul_f32 v[152:153], v[152:153], v[182:183] op_sel_hi:[1,0]
	v_pk_mul_f32 v[150:151], v[150:151], v[182:183] op_sel_hi:[1,0]
	v_pk_mul_f32 v[156:157], v[156:157], v[182:183] op_sel_hi:[1,0]
	v_pk_mul_f32 v[154:155], v[154:155], v[182:183] op_sel_hi:[1,0]
	v_pk_mul_f32 v[164:165], v[162:163], v[182:183] op_sel_hi:[1,0]
	v_pk_mul_f32 v[162:163], v[186:187], v[182:183] op_sel_hi:[1,0]
	v_mov_b64_e32 v[182:183], s[6:7]
	s_xor_b64 exec, exec, s[4:5]
	s_cbranch_execz .LBB0_691
	s_add_u32 s6, s14, s43
	s_addc_u32 s7, s15, 0
	v_and_b32_e32 v173, 0x7df, v167
	v_lshlrev_b32_e32 v167, s78, v167
	s_add_u32 s6, s6, s51
	v_and_b32_e32 v167, 0x7fe, v167
	v_lshrrev_b32_e32 v175, s41, v173
	s_addc_u32 s7, s7, 0
	v_lshl_add_u64 v[180:181], s[6:7], 0, v[178:179]
	v_add_lshl_u32 v182, v167, v175, 7
	v_mov_b32_e32 v183, v1
	v_lshl_add_u64 v[180:181], v[180:181], 0, v[182:183]
	v_mov_b32_e32 v175, v1
	v_lshl_add_u64 v[180:181], v[180:181], 0, v[174:175]
	v_cvt_pk_bf16_f32 v190, v150, v151
	v_cvt_pk_bf16_f32 v191, v152, v153
	v_cvt_pk_bf16_f32 v192, v154, v155
	v_cvt_pk_bf16_f32 v193, v156, v157
	v_cmp_le_i32_e32 vcc, s33, v173
	s_nop 1
	v_permlane16_swap_b32_e32 v190, v192
	v_permlane16_swap_b32_e32 v191, v193
	global_store_dwordx4 v[180:181], v[190:193], off
	s_nop 1
	v_cvt_pk_bf16_f32 v190, v158, v159
	v_cvt_pk_bf16_f32 v191, v160, v161
	s_and_b64 s[24:25], s[54:55], vcc
	s_mov_b64 s[64:65], s[0:1]
	v_cvt_pk_bf16_f32 v192, v162, v163
	v_cvt_pk_bf16_f32 v193, v164, v165
	s_nop 1
	v_permlane16_swap_b32_e32 v190, v192
	v_permlane16_swap_b32_e32 v191, v193
	global_store_dwordx4 v[180:181], v[190:193], off offset:64
	s_nop 1
	s_and_saveexec_b64 s[62:63], s[24:25]
	s_cbranch_execz .LBB0_690
	v_subrev_u32_e32 v180, s33, v173
	v_mov_b32_e32 v181, v1
	v_lshl_add_u64 v[180:181], v[176:177], 0, v[180:181]
	s_lshl_b64 s[6:7], s[52:53], 2
	v_lshl_add_u64 v[180:181], v[180:181], 1, v[0:1]
	s_add_u32 s6, s12, s6
	v_lshlrev_b64 v[180:181], s50, v[180:181]
	s_addc_u32 s7, s13, s7
	v_lshl_add_u64 v[180:181], v[180:181], 0, s[18:19]
	s_or_b64 s[64:65], s[0:1], exec

;     __device__ __forceinline__ void operator()(const f32x4 (&acc)[2][2][4][2], const pg8::Unit& u, int wr, int wc, int fr, int fq) const {
;     ...
;             for (int m = 0; m < 4; ++m) { const int row = row0 + ai * 128 + m * 16; const float rs = __builtin_amdgcn_rsqf(ss[row] * (1.f / DM) + EPS);
;                 f32x4 v[2][2]; float s = 0.f;
; #pragma unroll
;                 for (int bj = 0; bj < 2; ++bj)
; #pragma unroll
;                     for (int n = 0; n < 2; ++n) { v[bj][n] = acc[ai][bj][m][n] * rs; s += (v[bj][n][0] * v[bj][n][0] + v[bj][n][1] * v[bj][n][1]) + (v[bj][n][2] * v[bj][n][2] + v[bj][n][3] * v[bj][n][3]); }
;                 s += __shfl_xor(s, 16); s += __shfl_xor(s, 32);
.LBB0_693:
	s_or_b64 exec, exec, s[4:5]
	s_movk_i32 s0, 0x7f5f
	v_add_u32_e32 v167, 0xa0, v166
	v_cmp_lt_i32_e32 vcc, s0, v166
	s_mov_b64 s[0:1], 0
	v_mov_b32_e32 v150, v196
	v_fmamk_f32 v150, v150, 0x3a800000, v236
	v_rsq_f32_e32 v164, v150
	s_nop 0
	v_pk_mul_f32 v[150:151], v[34:35], v[164:165] op_sel_hi:[1,0]
	v_pk_mul_f32 v[152:153], v[36:37], v[164:165] op_sel_hi:[1,0]
	v_pk_mul_f32 v[156:157], v[150:151], v[150:151]
	v_pk_mul_f32 v[154:155], v[152:153], v[152:153]
	s_nop 0
	v_pk_mov_b32 v[158:159], v[156:157], v[154:155] op_sel:[1,0]
	v_mov_b32_e32 v157, v155
	v_pk_add_f32 v[154:155], v[158:159], v[156:157]
	v_pk_mul_f32 v[156:157], v[32:33], v[164:165] op_sel_hi:[1,0]
	v_pk_add_f32 v[180:181], v[154:155], v[154:155] op_sel_hi:[0,1]
	v_pk_mul_f32 v[154:155], v[30:31], v[164:165] op_sel_hi:[1,0]
	v_pk_mul_f32 v[158:159], v[156:157], v[156:157]
	v_pk_mul_f32 v[160:161], v[154:155], v[154:155]
	s_nop 0
	v_pk_mov_b32 v[162:163], v[160:161], v[158:159] op_sel:[1,0]
	v_mov_b32_e32 v161, v159
	v_pk_add_f32 v[158:159], v[162:163], v[160:161]
	v_pk_mul_f32 v[160:161], v[26:27], v[164:165] op_sel_hi:[1,0]
	v_pk_add_f32 v[182:183], v[158:159], v[158:159] op_sel_hi:[0,1]
	v_pk_mul_f32 v[158:159], v[28:29], v[164:165] op_sel_hi:[1,0]
	v_mul_f32_e32 v162, v160, v160
	v_pk_fma_f32 v[186:187], v[160:161], v[160:161], v[162:163] op_sel_hi:[1,1,0]
	v_mul_f32_e32 v162, v158, v158
	v_pk_fma_f32 v[188:189], v[158:159], v[158:159], v[162:163] op_sel_hi:[1,1,0]
	v_pk_mul_f32 v[162:163], v[24:25], v[164:165] op_sel_hi:[1,0]
	v_pk_mul_f32 v[164:165], v[22:23], v[164:165] op_sel_hi:[1,0]
	v_mul_f32_e32 v180, v162, v162
	v_mul_f32_e32 v186, v164, v164
	v_mul_f32_e32 v188, v165, v165
	v_mul_f32_e32 v182, v163, v163
	v_pk_add_f32 v[186:187], v[186:187], v[188:189]
	v_pk_add_f32 v[180:181], v[180:181], v[182:183]
	s_nop 0
	v_pk_add_f32 v[180:181], v[186:187], v[180:181]
	s_nop 0
	v_add_f32_e32 v173, v180, v181
	ds_bpermute_b32 v175, v184, v173
	s_waitcnt lgkmcnt(0)
	v_add_f32_e32 v173, v173, v175
	ds_bpermute_b32 v175, v185, v173
	s_and_saveexec_b64 s[4:5], vcc
	s_xor_b64 s[4:5], exec, s[4:5]
	s_cbranch_execz .LBB0_701
	s_mov_b32 s0, 0x8080
	v_cmp_gt_u32_e32 vcc, s0, v167
	s_mov_b64 s[62:63], 0
	s_and_saveexec_b64 s[0:1], vcc
	s_cbranch_execz .LBB0_700
	v_add_u32_e32 v167, 0xffff80a0, v166
	s_andn2_b64 vcc, exec, s[54:55]
	s_mov_b64 s[62:63], -1
	s_cbranch_vccnz .LBB0_697
	v_mov_b64_e32 v[180:181], s[60:61]
	v_mad_u64_u32 v[180:181], s[24:25], s70, v167, v[180:181]
	v_mov_b32_e32 v182, v181
	v_mad_u64_u32 v[182:183], s[24:25], s3, v167, v[182:183]
	v_mov_b32_e32 v181, v182
	s_lshl_b64 s[6:7], s[58:59], 2
	v_lshl_add_u64 v[180:181], v[180:181], 1, v[168:169]
	s_add_u32 s6, s12, s6
	v_lshlrev_b64 v[180:181], s50, v[180:181]
	s_addc_u32 s7, s13, s7
	v_lshl_add_u64 v[180:181], v[180:181], 0, s[18:19]
	s_mov_b64 s[62:63], 0

; __device__ __forceinline__ unsigned cvt_pk_bf16(float lo, float hi) { unsigned r; asm volatile("v_cvt_pk_bf16_f32 %0, %1, %2" : "=v"(r) : "v"(lo), "v"(hi)); return r; }
;     __device__ __forceinline__ void operator()(const f32x4 (&acc)[2][2][4][2], const pg8::Unit& u, int wr, int wc, int fr, int fq) const {
;     ...
;                 const float inv = (kind < 2) ? __builtin_amdgcn_rsqf(s * (1.f / 64.f) + EPS) : 1.f;
; #pragma unroll
;                 for (int bj = 0; bj < 2; ++bj)
; #pragma unroll
;                     for (int n = 0; n < 2; ++n) v[bj][n] = v[bj][n] * gv[bj][n] * inv;
;                 if (row < MPR) {
;                     const int b = row >> 11, sq = row & 2047, p = ((sq & (dil - 1)) << (11 - sh)) + (sq >> sh);
;                     bf16* dst = (bf16*)(wsb + boff) + ((size_t)(b * nh + idx) * 2048 + p) * 64;
; #pragma unroll
;                     for (int bj = 0; bj < 2; ++bj)
; #pragma unroll
;                         for (int n = 0; n < 2; ++n) { u32x2 w; w.x = cvt_pk_bf16(v[bj][n][0], v[bj][n][1]); w.y = cvt_pk_bf16(v[bj][n][2], v[bj][n][3]); *(u32x2*)(dst + 32 * bj + 16 * n + 4 * fq) = w; }
.LBB0_701:
	s_or_saveexec_b64 s[4:5], s[4:5]
	s_waitcnt lgkmcnt(0)
	v_add_f32_e32 v173, v173, v175
	v_fmamk_f32 v173, v173, 0x3c800000, v236
	v_rsq_f32_e32 v173, v173
	v_pk_mul_f32 v[186:187], v[138:139], v[160:161]
	v_pk_mul_f32 v[158:159], v[140:141], v[158:159]
	v_pk_mul_f32 v[150:151], v[146:147], v[150:151]
	v_cndmask_b32_e64 v182, 1.0, v173, s[10:11]
	v_pk_mul_f32 v[152:153], v[148:149], v[152:153]
	v_pk_mul_f32 v[154:155], v[142:143], v[154:155]
	v_pk_mul_f32 v[156:157], v[144:145], v[156:157]
	v_pk_mul_f32 v[160:161], v[158:159], v[182:183] op_sel_hi:[1,0]
	v_pk_mul_f32 v[158:159], v[186:187], v[182:183] op_sel_hi:[1,0]
	v_pk_mul_f32 v[186:187], v[134:135], v[164:165]
	v_pk_mul_f32 v[162:163], v[136:137], v[162:163]
	v_pk_mul_f32 v[152:153], v[152:153], v[182:183] op_sel_hi:[1,0]
	v_pk_mul_f32 v[150:151], v[150:151], v[182:183] op_sel_hi:[1,0]
	v_pk_mul_f32 v[156:157], v[156:157], v[182:183] op_sel_hi:[1,0]
	v_pk_mul_f32 v[154:155], v[154:155], v[182:183] op_sel_hi:[1,0]
	v_pk_mul_f32 v[164:165], v[162:163], v[182:183] op_sel_hi:[1,0]
	v_pk_mul_f32 v[162:163], v[186:187], v[182:183] op_sel_hi:[1,0]
	v_mov_b64_e32 v[182:183], s[6:7]
	s_xor_b64 exec, exec, s[4:5]
	s_cbranch_execz .LBB0_705
	s_add_u32 s6, s14, s43
	s_addc_u32 s7, s15, 0
	v_and_b32_e32 v173, 0x7ef, v167
	v_lshlrev_b32_e32 v167, s78, v167
	s_add_u32 s6, s6, s51
	v_and_b32_e32 v167, 0x7fe, v167
	v_lshrrev_b32_e32 v175, s41, v173
	s_addc_u32 s7, s7, 0
	v_lshl_add_u64 v[180:181], s[6:7], 0, v[178:179]
	v_add_lshl_u32 v182, v167, v175, 7
	v_mov_b32_e32 v183, v1
	v_lshl_add_u64 v[180:181], v[180:181], 0, v[182:183]
	v_mov_b32_e32 v175, v1
	v_lshl_add_u64 v[180:181], v[180:181], 0, v[174:175]
	v_cvt_pk_bf16_f32 v190, v150, v151
	v_cvt_pk_bf16_f32 v191, v152, v153
	v_cvt_pk_bf16_f32 v192, v154, v155
	v_cvt_pk_bf16_f32 v193, v156, v157
	v_cmp_le_i32_e32 vcc, s33, v173
	s_nop 1
	v_permlane16_swap_b32_e32 v190, v192
	v_permlane16_swap_b32_e32 v191, v193
	global_store_dwordx4 v[180:181], v[190:193], off
	s_nop 1
	v_cvt_pk_bf16_f32 v190, v158, v159
	v_cvt_pk_bf16_f32 v191, v160, v161
	s_and_b64 s[24:25], s[54:55], vcc
	s_mov_b64 s[64:65], s[0:1]
	v_cvt_pk_bf16_f32 v192, v162, v163
	v_cvt_pk_bf16_f32 v193, v164, v165
	s_nop 1
	v_permlane16_swap_b32_e32 v190, v192
	v_permlane16_swap_b32_e32 v191, v193
	global_store_dwordx4 v[180:181], v[190:193], off offset:64
	s_nop 1
	s_and_saveexec_b64 s[62:63], s[24:25]
	s_cbranch_execz .LBB0_704
	v_subrev_u32_e32 v180, s33, v173
	v_mov_b32_e32 v181, v1
	v_lshl_add_u64 v[180:181], v[176:177], 0, v[180:181]
	s_lshl_b64 s[6:7], s[52:53], 2
	v_lshl_add_u64 v[180:181], v[180:181], 1, v[0:1]
	s_add_u32 s6, s12, s6
	v_lshlrev_b64 v[180:181], s50, v[180:181]
	s_addc_u32 s7, s13, s7
	v_lshl_add_u64 v[180:181], v[180:181], 0, s[18:19]
	s_or_b64 s[64:65], s[0:1], exec

;     __device__ __forceinline__ void operator()(const f32x4 (&acc)[2][2][4][2], const pg8::Unit& u, int wr, int wc, int fr, int fq) const {
;     ...
;             for (int m = 0; m < 4; ++m) { const int row = row0 + ai * 128 + m * 16; const float rs = __builtin_amdgcn_rsqf(ss[row] * (1.f / DM) + EPS);
;                 f32x4 v[2][2]; float s = 0.f;
; #pragma unroll
;                 for (int bj = 0; bj < 2; ++bj)
; #pragma unroll
;                     for (int n = 0; n < 2; ++n) { v[bj][n] = acc[ai][bj][m][n] * rs; s += (v[bj][n][0] * v[bj][n][0] + v[bj][n][1] * v[bj][n][1]) + (v[bj][n][2] * v[bj][n][2] + v[bj][n][3] * v[bj][n][3]); }
;                 s += __shfl_xor(s, 16); s += __shfl_xor(s, 32);
.LBB0_707:
	s_or_b64 exec, exec, s[4:5]
	s_movk_i32 s0, 0x7f4f
	v_add_u32_e32 v167, 0xb0, v166
	v_cmp_lt_i32_e32 vcc, s0, v166
	s_mov_b64 s[0:1], 0
	v_mov_b32_e32 v150, v197
	v_fmamk_f32 v150, v150, 0x3a800000, v236
	v_rsq_f32_e32 v164, v150
	s_nop 0
	v_pk_mul_f32 v[150:151], v[18:19], v[164:165] op_sel_hi:[1,0]
	v_pk_mul_f32 v[152:153], v[20:21], v[164:165] op_sel_hi:[1,0]
	v_pk_mul_f32 v[156:157], v[150:151], v[150:151]
	v_pk_mul_f32 v[154:155], v[152:153], v[152:153]
	s_nop 0
	v_pk_mov_b32 v[158:159], v[156:157], v[154:155] op_sel:[1,0]
	v_mov_b32_e32 v157, v155
	v_pk_add_f32 v[154:155], v[158:159], v[156:157]
	v_pk_mul_f32 v[156:157], v[16:17], v[164:165] op_sel_hi:[1,0]
	v_pk_add_f32 v[170:171], v[154:155], v[154:155] op_sel_hi:[0,1]
	v_pk_mul_f32 v[154:155], v[14:15], v[164:165] op_sel_hi:[1,0]
	v_pk_mul_f32 v[158:159], v[156:157], v[156:157]
	v_pk_mul_f32 v[160:161], v[154:155], v[154:155]
	s_nop 0
	v_pk_mov_b32 v[162:163], v[160:161], v[158:159] op_sel:[1,0]
	v_mov_b32_e32 v161, v159
	v_pk_add_f32 v[158:159], v[162:163], v[160:161]
	v_pk_mul_f32 v[160:161], v[10:11], v[164:165] op_sel_hi:[1,0]
	v_pk_add_f32 v[180:181], v[158:159], v[158:159] op_sel_hi:[0,1]
	v_pk_mul_f32 v[158:159], v[12:13], v[164:165] op_sel_hi:[1,0]
	v_mul_f32_e32 v162, v160, v160
	v_pk_fma_f32 v[182:183], v[160:161], v[160:161], v[162:163] op_sel_hi:[1,1,0]
	v_mul_f32_e32 v162, v158, v158
	v_pk_fma_f32 v[186:187], v[158:159], v[158:159], v[162:163] op_sel_hi:[1,1,0]
	v_pk_mul_f32 v[162:163], v[8:9], v[164:165] op_sel_hi:[1,0]
	v_pk_mul_f32 v[164:165], v[6:7], v[164:165] op_sel_hi:[1,0]
	v_mul_f32_e32 v170, v162, v162
	v_mul_f32_e32 v182, v164, v164
	v_mul_f32_e32 v186, v165, v165
	v_mul_f32_e32 v180, v163, v163
	v_pk_add_f32 v[182:183], v[182:183], v[186:187]
	v_pk_add_f32 v[170:171], v[170:171], v[180:181]
	s_nop 0
	v_pk_add_f32 v[170:171], v[182:183], v[170:171]
	s_nop 0
	v_add_f32_e32 v170, v170, v171
	ds_bpermute_b32 v171, v184, v170
	s_waitcnt lgkmcnt(0)
	v_add_f32_e32 v173, v170, v171
	ds_bpermute_b32 v175, v185, v173
	s_and_saveexec_b64 s[4:5], vcc
	s_xor_b64 s[4:5], exec, s[4:5]
	s_cbranch_execz .LBB0_715
	s_mov_b32 s0, 0x8080
	v_cmp_gt_u32_e32 vcc, s0, v167
	s_mov_b64 s[62:63], 0
	s_and_saveexec_b64 s[0:1], vcc
	s_cbranch_execz .LBB0_714
	v_add_u32_e32 v0, 0xffff80b0, v166
	s_andn2_b64 vcc, exec, s[54:55]
	s_mov_b64 s[62:63], -1
	s_cbranch_vccnz .LBB0_711
	v_mov_b64_e32 v[170:171], s[60:61]
	v_mad_u64_u32 v[170:171], s[24:25], s70, v0, v[170:171]
	v_mov_b32_e32 v174, v171
	s_waitcnt lgkmcnt(0)
	v_mad_u64_u32 v[176:177], s[24:25], s3, v0, v[174:175]
	v_mov_b32_e32 v171, v176
	s_lshl_b64 s[6:7], s[58:59], 2
	v_lshl_add_u64 v[168:169], v[170:171], 1, v[168:169]
	s_add_u32 s6, s12, s6
	v_lshlrev_b64 v[168:169], s50, v[168:169]
	s_addc_u32 s7, s13, s7
	v_lshl_add_u64 v[170:171], v[168:169], 0, s[18:19]
	s_mov_b64 s[62:63], 0

; __device__ __forceinline__ unsigned cvt_pk_bf16(float lo, float hi) { unsigned r; asm volatile("v_cvt_pk_bf16_f32 %0, %1, %2" : "=v"(r) : "v"(lo), "v"(hi)); return r; }
;     __device__ __forceinline__ void operator()(const f32x4 (&acc)[2][2][4][2], const pg8::Unit& u, int wr, int wc, int fr, int fq) const {
;     ...
;                 const float inv = (kind < 2) ? __builtin_amdgcn_rsqf(s * (1.f / 64.f) + EPS) : 1.f;
; #pragma unroll
;                 for (int bj = 0; bj < 2; ++bj)
; #pragma unroll
;                     for (int n = 0; n < 2; ++n) v[bj][n] = v[bj][n] * gv[bj][n] * inv;
;                 if (row < MPR) {
;                     const int b = row >> 11, sq = row & 2047, p = ((sq & (dil - 1)) << (11 - sh)) + (sq >> sh);
;                     bf16* dst = (bf16*)(wsb + boff) + ((size_t)(b * nh + idx) * 2048 + p) * 64;
; #pragma unroll
;                     for (int bj = 0; bj < 2; ++bj)
; #pragma unroll
;                         for (int n = 0; n < 2; ++n) { u32x2 w; w.x = cvt_pk_bf16(v[bj][n][0], v[bj][n][1]); w.y = cvt_pk_bf16(v[bj][n][2], v[bj][n][3]); *(u32x2*)(dst + 32 * bj + 16 * n + 4 * fq) = w; }
.LBB0_715:
	s_or_saveexec_b64 s[4:5], s[4:5]
	s_waitcnt lgkmcnt(0)
	v_add_f32_e32 v168, v173, v175
	v_fmamk_f32 v168, v168, 0x3c800000, v236
	v_rsq_f32_e32 v168, v168
	v_pk_mul_f32 v[146:147], v[146:147], v[150:151]
	v_pk_mul_f32 v[148:149], v[148:149], v[152:153]
	v_pk_mul_f32 v[142:143], v[142:143], v[154:155]
	v_cndmask_b32_e64 v150, 1.0, v168, s[10:11]
	v_pk_mul_f32 v[144:145], v[144:145], v[156:157]
	v_pk_mul_f32 v[138:139], v[138:139], v[160:161]
	v_pk_mul_f32 v[140:141], v[140:141], v[158:159]
	v_pk_mul_f32 v[134:135], v[134:135], v[164:165]
	v_pk_mul_f32 v[136:137], v[136:137], v[162:163]
	v_pk_mul_f32 v[148:149], v[148:149], v[150:151] op_sel_hi:[1,0]
	v_pk_mul_f32 v[146:147], v[146:147], v[150:151] op_sel_hi:[1,0]
	v_pk_mul_f32 v[144:145], v[144:145], v[150:151] op_sel_hi:[1,0]
	v_pk_mul_f32 v[142:143], v[142:143], v[150:151] op_sel_hi:[1,0]
	v_pk_mul_f32 v[140:141], v[140:141], v[150:151] op_sel_hi:[1,0]
	v_pk_mul_f32 v[138:139], v[138:139], v[150:151] op_sel_hi:[1,0]
	v_pk_mul_f32 v[136:137], v[136:137], v[150:151] op_sel_hi:[1,0]
	v_pk_mul_f32 v[134:135], v[134:135], v[150:151] op_sel_hi:[1,0]
	v_mov_b64_e32 v[150:151], s[6:7]
	s_xor_b64 exec, exec, s[4:5]
	s_cbranch_execz .LBB0_719
	s_add_u32 s3, s14, s43
	s_addc_u32 s7, s15, 0
	v_and_b32_e32 v150, 0x7ff, v167
	v_lshlrev_b32_e32 v151, s78, v167
	s_add_u32 s6, s3, s51
	v_and_b32_e32 v151, 0x7fe, v151
	v_lshrrev_b32_e32 v154, s41, v150
	s_addc_u32 s7, s7, 0
	v_lshl_add_u64 v[152:153], s[6:7], 0, v[178:179]
	v_add_lshl_u32 v154, v151, v154, 7
	v_mov_b32_e32 v155, v1
	v_lshl_add_u64 v[152:153], v[152:153], 0, v[154:155]
	v_mov_b32_e32 v175, v1
	v_lshl_add_u64 v[152:153], v[152:153], 0, v[174:175]
	v_cvt_pk_bf16_f32 v190, v146, v147
	v_cvt_pk_bf16_f32 v191, v148, v149
	v_cvt_pk_bf16_f32 v192, v142, v143
	v_cvt_pk_bf16_f32 v193, v144, v145
	v_cmp_le_i32_e32 vcc, s33, v150
	s_nop 1
	v_permlane16_swap_b32_e32 v190, v192
	v_permlane16_swap_b32_e32 v191, v193
	global_store_dwordx4 v[152:153], v[190:193], off
	s_nop 1
	v_cvt_pk_bf16_f32 v190, v138, v139
	v_cvt_pk_bf16_f32 v191, v140, v141
	s_and_b64 s[24:25], s[54:55], vcc
	s_mov_b64 s[54:55], s[0:1]
	v_cvt_pk_bf16_f32 v192, v134, v135
	v_cvt_pk_bf16_f32 v193, v136, v137
	s_nop 1
	v_permlane16_swap_b32_e32 v190, v192
	v_permlane16_swap_b32_e32 v191, v193
	global_store_dwordx4 v[152:153], v[190:193], off offset:64
	s_nop 1
	s_and_saveexec_b64 s[10:11], s[24:25]
	s_cbranch_execz .LBB0_718
	v_subrev_u32_e32 v150, s33, v150
	v_mov_b32_e32 v151, v1
	v_lshl_add_u64 v[150:151], v[176:177], 0, v[150:151]
	s_lshl_b64 s[6:7], s[52:53], 2
	v_lshl_add_u64 v[150:151], v[150:151], 1, v[0:1]
	s_add_u32 s6, s12, s6
	v_lshlrev_b64 v[150:151], s50, v[150:151]
	s_addc_u32 s7, s13, s7
	v_lshl_add_u64 v[170:171], v[150:151], 0, s[18:19]
	s_or_b64 s[54:55], s[0:1], exec
